# xor-1/2/4/8 reduction steps in E1, E2 and norm phases done with DPP adds instead of ds_bpermute round trips
# speedup vs baseline: 1.0040x; 1.0040x over previous
; __device__ __forceinline__ float bflo(unsigned w) { return __uint_as_float(w << 16); }
; __device__ __forceinline__ float bfhi(unsigned w) { return __uint_as_float(w & 0xffff0000u); }
; __device__ __forceinline__ unsigned cvt_pk_bf16(float lo, float hi) { unsigned r; asm volatile("v_cvt_pk_bf16_f32 %0, %1, %2" : "=v"(r) : "v"(lo), "v"(hi)); return r; }
; __device__ __forceinline__ void e1_row(CArgs& a, int l, int r, int lane, int dup, const E1Regs& g) {
;     ...
;       for (int t = 0; t < 3; ++t) { const int hh = 4 * t + hsub; const u32x4 w = g.hq[t];
;           float x[8] = {bflo(w.x), bfhi(w.x), bflo(w.y), bfhi(w.y), bflo(w.z), bfhi(w.z), bflo(w.w), bfhi(w.w)};
;           float ss = 0.f;
; #pragma unroll
;           for (int e = 0; e < 8; ++e) ss += x[e] * x[e];
; #pragma unroll
;           for (int m = 1; m < 16; m <<= 1) ss += __shfl_xor(ss, m);
;           const float rs = rsqrtf(ss * (1.f / 128.f) + EPS) * (hh < 8 ? QSCALE_A : 1.f);
;           const float* gg = a.in[hh < 8 ? I_AQN : I_AKN] + l * 128 + 8 * li;
;           const f32x4 ga = *(const f32x4*)gg, gb = *(const f32x4*)(gg + 4);
;           float y[8] = {x[0] * rs * ga.x, x[1] * rs * ga.y, x[2] * rs * ga.z, x[3] * rs * ga.w, x[4] * rs * gb.x, x[5] * rs * gb.y, x[6] * rs * gb.z, x[7] * rs * gb.w};
;           if (lat) {
; #pragma unroll
;               for (int e = 0; e < 8; ++e) { const float p = __shfl_xor(y[e], 4); y[e] = second ? (p * sn[e] + y[e] * cs[e]) : (y[e] * cs[e] - p * sn[e]); } }
;           u32x4 o; o.x = cvt_pk_bf16(y[0], y[1]); o.y = cvt_pk_bf16(y[2], y[3]); o.z = cvt_pk_bf16(y[4], y[5]); o.w = cvt_pk_bf16(y[6], y[7]);
;           if (hh < 10) *((u32x4*)(P + t * 512) + lane) = o; } }
.LBB0_42:
	s_or_b64 exec, exec, s[20:21]
	v_mov_b64_e32 v[76:77], v[110:111]
	v_mov_b64_e32 v[78:79], v[112:113]
	v_mov_b64_e32 v[96:97], v[114:115]
	v_mov_b64_e32 v[98:99], v[116:117]
	v_and_b32_e32 v45, 64, v223
	v_xor_b32_e32 v91, 1, v223
	s_waitcnt vmcnt(0)
	v_lshlrev_b32_e32 v100, 16, v30
	v_and_b32_e32 v101, 0xffff0000, v30
	v_add_u32_e32 v95, 64, v45
	v_lshlrev_b32_e32 v30, 16, v31
	v_and_b32_e32 v31, 0xffff0000, v31
	v_pk_mul_f32 v[92:93], v[100:101], v[100:101]
	v_cmp_lt_i32_e64 s[52:53], v91, v95
	v_pk_mul_f32 v[104:105], v[30:31], v[30:31]
	v_add_f32_e32 v92, v92, v93
	v_cndmask_b32_e64 v45, v223, v91, s[52:53]
	v_lshlrev_b32_e32 v102, 16, v32
	v_and_b32_e32 v103, 0xffff0000, v32
	v_lshlrev_b32_e32 v91, 2, v45
	v_add_f32_e32 v45, v104, v92
	v_pk_mul_f32 v[106:107], v[102:103], v[102:103]
	v_add_f32_e32 v45, v105, v45
	v_lshlrev_b32_e32 v32, 16, v33
	v_and_b32_e32 v33, 0xffff0000, v33
	v_add_f32_e32 v45, v106, v45
	v_pk_mul_f32 v[108:109], v[32:33], v[32:33]
	v_add_f32_e32 v45, v107, v45
	v_add_f32_e32 v45, v108, v45
	v_add_f32_e32 v45, v109, v45
	s_nop 1
	v_xor_b32_e32 v92, 2, v223
	v_cmp_lt_i32_e64 s[52:53], v92, v95
	v_add_f32_dpp v45, v45, v45 quad_perm:[1,0,3,2] row_mask:0xf bank_mask:0xf
	v_cndmask_b32_e64 v92, v223, v92, s[52:53]
	v_lshlrev_b32_e32 v92, 2, v92
	s_nop 1
	v_xor_b32_e32 v93, 4, v223
	v_cmp_lt_i32_e64 s[52:53], v93, v95
	v_add_f32_dpp v104, v45, v45 quad_perm:[2,3,0,1] row_mask:0xf bank_mask:0xf
	v_cndmask_b32_e64 v93, v223, v93, s[52:53]
	v_lshlrev_b32_e32 v93, 2, v93
	s_nop 1
	v_xor_b32_e32 v45, 8, v223
	v_cmp_lt_i32_e64 s[52:53], v45, v95
	v_add_f32_dpp v104, v104, v104 row_half_mirror row_mask:0xf bank_mask:0xf
	v_cndmask_b32_e64 v45, v223, v45, s[52:53]
	v_lshlrev_b32_e32 v45, 2, v45
	s_nop 1
	v_add_f32_dpp v104, v104, v104 row_mirror row_mask:0xf bank_mask:0xf
	v_fmamk_f32 v104, v104, 0x3c000000, v216
	v_mul_f32_e32 v105, 0x4b800000, v104
	v_cmp_gt_f32_e64 s[52:53], s26, v104
	s_nop 1
	v_cndmask_b32_e64 v104, v104, v105, s[52:53]
	v_rsq_f32_e32 v104, v104
	s_nop 0
	v_mul_f32_e32 v105, 0x45800000, v104
	v_cndmask_b32_e64 v104, v104, v105, s[52:53]
	v_mul_f32_e32 v104, 0x3e0293ee, v104
	v_pk_mul_f32 v[100:101], v[104:105], v[100:101] op_sel_hi:[0,1]
	v_pk_mul_f32 v[106:107], v[104:105], v[30:31] op_sel_hi:[0,1]
	v_pk_mul_f32 v[102:103], v[104:105], v[102:103] op_sel_hi:[0,1]
	v_pk_mul_f32 v[104:105], v[104:105], v[32:33] op_sel_hi:[0,1]
	v_pk_mul_f32 v[30:31], v[76:77], v[100:101]
	v_pk_mul_f32 v[32:33], v[78:79], v[106:107]
	v_pk_mul_f32 v[76:77], v[96:97], v[102:103]
	v_pk_mul_f32 v[78:79], v[98:99], v[104:105]
	s_and_saveexec_b64 s[20:21], s[48:49]
	s_cbranch_execz .LBB0_44
	ds_bpermute_b32 v96, v93, v30
	ds_bpermute_b32 v97, v93, v31
	ds_bpermute_b32 v98, v93, v32
	ds_bpermute_b32 v99, v93, v33
	ds_bpermute_b32 v100, v93, v76
	ds_bpermute_b32 v101, v93, v77
	ds_bpermute_b32 v102, v93, v78
	ds_bpermute_b32 v103, v93, v79
	s_waitcnt lgkmcnt(6)
	v_pk_mul_f32 v[96:97], v[74:75], v[96:97]
	s_waitcnt lgkmcnt(4)
	v_pk_mul_f32 v[98:99], v[72:73], v[98:99]
	s_waitcnt lgkmcnt(2)
	v_pk_mul_f32 v[100:101], v[70:71], v[100:101]
	v_cndmask_b32_e64 v97, v97, -v97, s[38:39]
	s_waitcnt lgkmcnt(0)
	v_pk_mul_f32 v[102:103], v[68:69], v[102:103]
	v_cndmask_b32_e64 v96, v96, -v96, s[38:39]
	v_cndmask_b32_e64 v99, v99, -v99, s[38:39]
	v_cndmask_b32_e64 v98, v98, -v98, s[38:39]
	v_cndmask_b32_e64 v101, v101, -v101, s[38:39]
	v_cndmask_b32_e64 v100, v100, -v100, s[38:39]
	v_cndmask_b32_e64 v102, v102, -v102, s[38:39]
	v_cndmask_b32_e64 v103, v103, -v103, s[38:39]
	v_pk_fma_f32 v[78:79], v[66:67], v[78:79], v[102:103]
	v_pk_fma_f32 v[76:77], v[64:65], v[76:77], v[100:101]
	v_pk_fma_f32 v[32:33], v[62:63], v[32:33], v[98:99]
	v_pk_fma_f32 v[30:31], v[60:61], v[30:31], v[96:97]
; __device__ __forceinline__ float bflo(unsigned w) { return __uint_as_float(w << 16); }
; __device__ __forceinline__ float bfhi(unsigned w) { return __uint_as_float(w & 0xffff0000u); }
; __device__ __forceinline__ unsigned cvt_pk_bf16(float lo, float hi) { unsigned r; asm volatile("v_cvt_pk_bf16_f32 %0, %1, %2" : "=v"(r) : "v"(lo), "v"(hi)); return r; }
; __device__ __forceinline__ void e1_row(CArgs& a, int l, int r, int lane, int dup, const E1Regs& g) {
;     ...
;       for (int t = 0; t < 3; ++t) { const int hh = 4 * t + hsub; const u32x4 w = g.hq[t];
;           float x[8] = {bflo(w.x), bfhi(w.x), bflo(w.y), bfhi(w.y), bflo(w.z), bfhi(w.z), bflo(w.w), bfhi(w.w)};
;           float ss = 0.f;
; #pragma unroll
;           for (int e = 0; e < 8; ++e) ss += x[e] * x[e];
; #pragma unroll
;           for (int m = 1; m < 16; m <<= 1) ss += __shfl_xor(ss, m);
;           const float rs = rsqrtf(ss * (1.f / 128.f) + EPS) * (hh < 8 ? QSCALE_A : 1.f);
;           const float* gg = a.in[hh < 8 ? I_AQN : I_AKN] + l * 128 + 8 * li;
;           const f32x4 ga = *(const f32x4*)gg, gb = *(const f32x4*)(gg + 4);
;           float y[8] = {x[0] * rs * ga.x, x[1] * rs * ga.y, x[2] * rs * ga.z, x[3] * rs * ga.w, x[4] * rs * gb.x, x[5] * rs * gb.y, x[6] * rs * gb.z, x[7] * rs * gb.w};
;           if (lat) {
; #pragma unroll
;               for (int e = 0; e < 8; ++e) { const float p = __shfl_xor(y[e], 4); y[e] = second ? (p * sn[e] + y[e] * cs[e]) : (y[e] * cs[e] - p * sn[e]); } }
;           u32x4 o; o.x = cvt_pk_bf16(y[0], y[1]); o.y = cvt_pk_bf16(y[2], y[3]); o.z = cvt_pk_bf16(y[4], y[5]); o.w = cvt_pk_bf16(y[6], y[7]);
;           if (hh < 10) *((u32x4*)(P + t * 512) + lane) = o; } }
.LBB0_44:
	s_or_b64 exec, exec, s[20:21]
	v_cvt_pk_bf16_f32 v30, v30, v31
	v_cvt_pk_bf16_f32 v31, v32, v33
	v_cvt_pk_bf16_f32 v32, v76, v77
	v_cvt_pk_bf16_f32 v33, v78, v79
	global_store_dwordx4 v[54:55], v[30:33], off
	s_nop 1
	v_mov_b64_e32 v[30:31], v[110:111]
	v_mov_b64_e32 v[32:33], v[112:113]
	s_nop 0
	v_mov_b64_e32 v[76:77], v[114:115]
	v_mov_b64_e32 v[78:79], v[116:117]
	v_lshlrev_b32_e32 v96, 16, v26
	v_and_b32_e32 v97, 0xffff0000, v26
	v_lshlrev_b32_e32 v26, 16, v27
	v_and_b32_e32 v27, 0xffff0000, v27
	v_pk_mul_f32 v[100:101], v[96:97], v[96:97]
	v_pk_mul_f32 v[102:103], v[26:27], v[26:27]
	v_add_f32_e32 v100, v100, v101
	v_lshlrev_b32_e32 v98, 16, v28
	v_and_b32_e32 v99, 0xffff0000, v28
	v_add_f32_e32 v100, v102, v100
	v_pk_mul_f32 v[104:105], v[98:99], v[98:99]
	v_add_f32_e32 v100, v103, v100
	v_lshlrev_b32_e32 v28, 16, v29
	v_and_b32_e32 v29, 0xffff0000, v29
	v_add_f32_e32 v100, v104, v100
	v_pk_mul_f32 v[106:107], v[28:29], v[28:29]
	v_add_f32_e32 v100, v105, v100
	v_add_f32_e32 v100, v106, v100
	v_add_f32_e32 v100, v107, v100
	s_nop 1
	v_add_f32_dpp v100, v100, v100 quad_perm:[1,0,3,2] row_mask:0xf bank_mask:0xf
	s_nop 1
	v_add_f32_dpp v100, v100, v100 quad_perm:[2,3,0,1] row_mask:0xf bank_mask:0xf
	s_nop 1
	v_add_f32_dpp v100, v100, v100 row_half_mirror row_mask:0xf bank_mask:0xf
	s_nop 1
	v_add_f32_dpp v100, v100, v100 row_mirror row_mask:0xf bank_mask:0xf
	v_fmamk_f32 v100, v100, 0x3c000000, v216
	v_mul_f32_e32 v101, 0x4b800000, v100
	v_cmp_gt_f32_e64 s[52:53], s26, v100
	s_nop 1
	v_cndmask_b32_e64 v100, v100, v101, s[52:53]
	v_rsq_f32_e32 v100, v100
	s_nop 0
	v_mul_f32_e32 v101, 0x45800000, v100
	v_cndmask_b32_e64 v100, v100, v101, s[52:53]
	v_mul_f32_e32 v100, 0x3e0293ee, v100
	v_pk_mul_f32 v[96:97], v[100:101], v[96:97] op_sel_hi:[0,1]
	v_pk_mul_f32 v[102:103], v[100:101], v[26:27] op_sel_hi:[0,1]
	v_pk_mul_f32 v[98:99], v[100:101], v[98:99] op_sel_hi:[0,1]
	v_pk_mul_f32 v[100:101], v[100:101], v[28:29] op_sel_hi:[0,1]
	v_pk_mul_f32 v[26:27], v[30:31], v[96:97]
	v_pk_mul_f32 v[28:29], v[32:33], v[102:103]
	v_pk_mul_f32 v[30:31], v[76:77], v[98:99]
	v_pk_mul_f32 v[32:33], v[78:79], v[100:101]
	s_and_saveexec_b64 s[20:21], s[48:49]
	s_cbranch_execz .LBB0_46
	ds_bpermute_b32 v76, v93, v26
	ds_bpermute_b32 v77, v93, v27
	ds_bpermute_b32 v78, v93, v28
	ds_bpermute_b32 v79, v93, v29
	ds_bpermute_b32 v96, v93, v30
	ds_bpermute_b32 v97, v93, v31
	ds_bpermute_b32 v98, v93, v32
	ds_bpermute_b32 v99, v93, v33
	s_waitcnt lgkmcnt(6)
	v_pk_mul_f32 v[76:77], v[74:75], v[76:77]
	s_waitcnt lgkmcnt(4)
	v_pk_mul_f32 v[78:79], v[72:73], v[78:79]
	s_waitcnt lgkmcnt(2)
	v_pk_mul_f32 v[96:97], v[70:71], v[96:97]
	v_cndmask_b32_e64 v77, v77, -v77, s[38:39]
	s_waitcnt lgkmcnt(0)
	v_pk_mul_f32 v[98:99], v[68:69], v[98:99]
	v_cndmask_b32_e64 v76, v76, -v76, s[38:39]
	v_cndmask_b32_e64 v79, v79, -v79, s[38:39]
	v_cndmask_b32_e64 v78, v78, -v78, s[38:39]
	v_cndmask_b32_e64 v97, v97, -v97, s[38:39]
	v_cndmask_b32_e64 v96, v96, -v96, s[38:39]
	v_cndmask_b32_e64 v98, v98, -v98, s[38:39]
	v_cndmask_b32_e64 v99, v99, -v99, s[38:39]
	v_pk_fma_f32 v[32:33], v[66:67], v[32:33], v[98:99]
	v_pk_fma_f32 v[30:31], v[64:65], v[30:31], v[96:97]
	v_pk_fma_f32 v[28:29], v[62:63], v[28:29], v[78:79]
	v_pk_fma_f32 v[26:27], v[60:61], v[26:27], v[76:77]
.LBB0_46:
	s_or_b64 exec, exec, s[20:21]
	v_cvt_pk_bf16_f32 v26, v26, v27
	v_cvt_pk_bf16_f32 v27, v28, v29
	v_cvt_pk_bf16_f32 v28, v30, v31
	v_cvt_pk_bf16_f32 v29, v32, v33
	global_store_dwordx4 v[54:55], v[26:29], off offset:1024
	s_nop 1
	v_mov_b64_e32 v[26:27], v[118:119]
	v_mov_b64_e32 v[28:29], v[120:121]
	s_nop 0
	v_mov_b64_e32 v[30:31], v[122:123]
	v_mov_b64_e32 v[32:33], v[124:125]
	v_lshlrev_b32_e32 v76, 16, v22
	v_and_b32_e32 v77, 0xffff0000, v22
	v_lshlrev_b32_e32 v22, 16, v23
	v_and_b32_e32 v23, 0xffff0000, v23
	v_pk_mul_f32 v[96:97], v[76:77], v[76:77]
	v_pk_mul_f32 v[98:99], v[22:23], v[22:23]
	v_add_f32_e32 v96, v96, v97
	v_lshlrev_b32_e32 v78, 16, v24
	v_and_b32_e32 v79, 0xffff0000, v24
	v_add_f32_e32 v96, v98, v96
	v_pk_mul_f32 v[100:101], v[78:79], v[78:79]
	v_add_f32_e32 v96, v99, v96
	v_lshlrev_b32_e32 v24, 16, v25
	v_and_b32_e32 v25, 0xffff0000, v25
	v_add_f32_e32 v96, v100, v96
	v_pk_mul_f32 v[102:103], v[24:25], v[24:25]
	v_add_f32_e32 v96, v101, v96
	v_add_f32_e32 v96, v102, v96
	v_add_f32_e32 v96, v103, v96
	s_nop 1
	v_add_f32_dpp v96, v96, v96 quad_perm:[1,0,3,2] row_mask:0xf bank_mask:0xf
	s_nop 1
	v_add_f32_dpp v96, v96, v96 quad_perm:[2,3,0,1] row_mask:0xf bank_mask:0xf
	s_nop 1
	v_add_f32_dpp v96, v96, v96 row_half_mirror row_mask:0xf bank_mask:0xf
	s_nop 1
	v_add_f32_dpp v96, v96, v96 row_mirror row_mask:0xf bank_mask:0xf
	v_fmamk_f32 v96, v96, 0x3c000000, v216
	v_mul_f32_e32 v97, 0x4b800000, v96
	v_cmp_gt_f32_e64 s[52:53], s26, v96
	s_nop 1
	v_cndmask_b32_e64 v96, v96, v97, s[52:53]
	v_rsq_f32_e32 v96, v96
	s_nop 0
	v_mul_f32_e32 v97, 0x45800000, v96
	v_cndmask_b32_e64 v96, v96, v97, s[52:53]
	v_pk_mul_f32 v[76:77], v[96:97], v[76:77] op_sel_hi:[0,1]
	v_pk_mul_f32 v[98:99], v[96:97], v[22:23] op_sel_hi:[0,1]
	v_pk_mul_f32 v[78:79], v[96:97], v[78:79] op_sel_hi:[0,1]
	v_pk_mul_f32 v[96:97], v[96:97], v[24:25] op_sel_hi:[0,1]
	v_pk_mul_f32 v[22:23], v[26:27], v[76:77]
	v_pk_mul_f32 v[24:25], v[28:29], v[98:99]
	v_pk_mul_f32 v[26:27], v[30:31], v[78:79]
	v_pk_mul_f32 v[28:29], v[32:33], v[96:97]
	s_and_saveexec_b64 s[20:21], s[48:49]
	s_cbranch_execz .LBB0_48
	ds_bpermute_b32 v32, v93, v24
	ds_bpermute_b32 v33, v93, v25
	ds_bpermute_b32 v30, v93, v22
	ds_bpermute_b32 v31, v93, v23
	s_waitcnt lgkmcnt(2)
	v_pk_mul_f32 v[32:33], v[72:73], v[32:33]
	ds_bpermute_b32 v72, v93, v26
	ds_bpermute_b32 v73, v93, v27
	s_waitcnt lgkmcnt(2)
	v_pk_mul_f32 v[30:31], v[74:75], v[30:31]
	v_cndmask_b32_e64 v33, v33, -v33, s[38:39]
	v_cndmask_b32_e64 v31, v31, -v31, s[38:39]
	v_cndmask_b32_e64 v30, v30, -v30, s[38:39]
	s_waitcnt lgkmcnt(0)
	v_pk_mul_f32 v[70:71], v[70:71], v[72:73]
	ds_bpermute_b32 v72, v93, v28
	ds_bpermute_b32 v73, v93, v29
	v_cndmask_b32_e64 v32, v32, -v32, s[38:39]
	v_cndmask_b32_e64 v71, v71, -v71, s[38:39]
	v_cndmask_b32_e64 v70, v70, -v70, s[38:39]
	v_pk_fma_f32 v[26:27], v[64:65], v[26:27], v[70:71]
	s_waitcnt lgkmcnt(0)
	v_pk_mul_f32 v[68:69], v[68:69], v[72:73]
	v_pk_fma_f32 v[24:25], v[62:63], v[24:25], v[32:33]
	v_cndmask_b32_e64 v68, v68, -v68, s[38:39]
	v_cndmask_b32_e64 v69, v69, -v69, s[38:39]
	v_pk_fma_f32 v[28:29], v[66:67], v[28:29], v[68:69]
	v_pk_fma_f32 v[22:23], v[60:61], v[22:23], v[30:31]

; __device__ __forceinline__ float bflo(unsigned w) { return __uint_as_float(w << 16); }
; __device__ __forceinline__ float bfhi(unsigned w) { return __uint_as_float(w & 0xffff0000u); }
; __device__ __forceinline__ unsigned cvt_pk_bf16(float lo, float hi) { unsigned r; asm volatile("v_cvt_pk_bf16_f32 %0, %1, %2" : "=v"(r) : "v"(lo), "v"(hi)); return r; }
; __device__ __forceinline__ void e1_row(CArgs& a, int l, int r, int lane, int dup, const E1Regs& g) {
;     ...
;     { const u32x4 w = g.cqw;
;         float x[8] = {bflo(w.x), bfhi(w.x), bflo(w.y), bfhi(w.y), bflo(w.z), bfhi(w.z), bflo(w.w), bfhi(w.w)};
;         float ss = 0.f;
; #pragma unroll
;         for (int e = 0; e < 8; ++e) ss += x[e] * x[e];
;         const float rs = rsqrtf(wave_sum(ss) * (1.f / 512.f) + EPS);
;         const float* gg = a.in[I_BQLN] + l * 512 + 8 * lane;
;         u32x4 o; o.x = cvt_pk_bf16(x[0] * rs * gg[0], x[1] * rs * gg[1]); o.y = cvt_pk_bf16(x[2] * rs * gg[2], x[3] * rs * gg[3]);
;         o.z = cvt_pk_bf16(x[4] * rs * gg[4], x[5] * rs * gg[5]); o.w = cvt_pk_bf16(x[6] * rs * gg[6], x[7] * rs * gg[7]); *((u32x4*)(P + C_BCQ) + lane) = o;
;     }
;     { const u32x2 w = g.ckw;
;         float x[4] = {bflo(w.x), bfhi(w.x), bflo(w.y), bfhi(w.y)};
;         const float rs = rsqrtf(wave_sum(x[0] * x[0] + x[1] * x[1] + x[2] * x[2] + x[3] * x[3]) * (1.f / 256.f) + EPS);
;         const float* gg = a.in[I_BKVLN] + l * 256 + 4 * lane;
;         u32x2 o; o.x = cvt_pk_bf16(x[0] * rs * gg[0], x[1] * rs * gg[1]); o.y = cvt_pk_bf16(x[2] * rs * gg[2], x[3] * rs * gg[3]); *((u32x2*)(P + C_BCKV) + lane) = o;
;     }
;     { const unsigned w = g.krw;
;         float x0 = lane < 32 ? bflo(w) : 0.f, x1 = lane < 32 ? bfhi(w) : 0.f;
;         const float rs = rsqrtf(wave_sum(x0 * x0 + x1 * x1) * (1.f / 64.f) + EPS);
;         const float* gg = a.in[I_BKRN] + l * 64 + 2 * (lane & 31);
;         float y0 = x0 * rs * gg[0], y1 = x1 * rs * gg[1];
;         if (lat) rope64(y0, y1, lane, prow, pcol);
;         if (lane < 32) *((unsigned*)(P + C_BKR) + lane) = cvt_pk_bf16(y0, y1);
;     }
.LBB0_50:
	s_or_b64 exec, exec, s[14:15]
	v_and_b32_e32 v27, 0xffff0000, v18
	v_lshlrev_b32_e32 v26, 16, v18
	v_mul_f32_e32 v30, v27, v27
	v_lshlrev_b32_e32 v28, 16, v19
	v_fmac_f32_e32 v30, v26, v26
	v_and_b32_e32 v29, 0xffff0000, v19
	v_fmac_f32_e32 v30, v28, v28
	v_and_b32_e32 v24, 0xffff0000, v20
	v_lshlrev_b32_e32 v25, 16, v20
	v_fmac_f32_e32 v30, v29, v29
	v_pk_mul_f32 v[18:19], v[24:25], v[24:25]
	s_mov_b64 s[4:5], 0x1000
	v_add_f32_e32 v19, v19, v30
	v_add_f32_e32 v30, v18, v19
	v_and_b32_e32 v18, 0xffff0000, v21
	v_lshlrev_b32_e32 v19, 16, v21
	v_pk_mul_f32 v[20:21], v[18:19], v[18:19]
	v_lshl_add_u64 v[22:23], v[58:59], 0, s[4:5]
	v_add_f32_e32 v21, v21, v30
	v_add_f32_e32 v20, v20, v21
	s_nop 1
	v_add_f32_dpp v20, v20, v20 quad_perm:[1,0,3,2] row_mask:0xf bank_mask:0xf
	s_nop 1
	v_add_f32_dpp v20, v20, v20 quad_perm:[2,3,0,1] row_mask:0xf bank_mask:0xf
	s_nop 1
	v_add_f32_dpp v20, v20, v20 row_half_mirror row_mask:0xf bank_mask:0xf
	s_nop 1
	v_add_f32_dpp v20, v20, v20 row_mirror row_mask:0xf bank_mask:0xf
	v_xor_b32_e32 v21, 16, v223
	v_cmp_lt_i32_e64 s[52:53], v21, v95
	s_nop 1
	v_cndmask_b32_e64 v21, v223, v21, s[52:53]
	v_lshlrev_b32_e32 v60, 2, v21
	ds_bpermute_b32 v21, v60, v20
	s_waitcnt lgkmcnt(0)
	v_add_f32_e32 v20, v20, v21
	v_xor_b32_e32 v21, 32, v223
	v_cmp_lt_i32_e64 s[52:53], v21, v95
	s_nop 1
	v_cndmask_b32_e64 v21, v223, v21, s[52:53]
	v_lshlrev_b32_e32 v61, 2, v21
	ds_bpermute_b32 v21, v61, v20
	s_waitcnt lgkmcnt(0)
	v_add_f32_e32 v20, v20, v21
	v_fmamk_f32 v20, v20, 0x3b000000, v216
	v_cmp_gt_f32_e64 s[52:53], s26, v20
	v_mul_f32_e32 v21, 0x4b800000, v20
	s_nop 0
	v_cndmask_b32_e64 v20, v20, v21, s[52:53]
	v_rsq_f32_e32 v20, v20
	s_nop 0
	v_mul_f32_e32 v21, 0x45800000, v20
	v_cndmask_b32_e64 v30, v20, v21, s[52:53]
	v_mov_b64_e32 v[20:21], v[126:127]
	v_mul_f32_e32 v26, v30, v26
	v_mul_f32_e32 v25, v30, v25
	v_mul_f32_e32 v24, v30, v24
	v_mul_f32_e32 v19, v30, v19
	v_mul_f32_e32 v18, v30, v18
	v_mul_f32_e32 v20, v20, v26
	v_mul_f32_e32 v26, v30, v27
	v_mul_f32_e32 v21, v21, v26
	v_cvt_pk_bf16_f32 v26, v20, v21
	v_mov_b64_e32 v[20:21], v[128:129]
	v_mul_f32_e32 v27, v30, v28
	v_mul_f32_e32 v20, v20, v27
	v_mul_f32_e32 v27, v30, v29
	v_mul_f32_e32 v21, v21, v27
	v_cvt_pk_bf16_f32 v27, v20, v21
	v_mov_b64_e32 v[20:21], v[130:131]
	v_mul_f32_e32 v20, v20, v25
	v_mul_f32_e32 v21, v21, v24
	v_cvt_pk_bf16_f32 v28, v20, v21
	v_mov_b64_e32 v[20:21], v[132:133]
	v_mul_f32_e32 v19, v19, v20
	v_mul_f32_e32 v18, v18, v21
	v_lshlrev_b32_e32 v20, 16, v56
	v_and_b32_e32 v21, 0xffff0000, v56
	v_cvt_pk_bf16_f32 v29, v19, v18
	v_pk_mul_f32 v[24:25], v[20:21], v[20:21]
	v_and_b32_e32 v18, 0xffff0000, v57
	v_lshlrev_b32_e32 v19, 16, v57
	global_store_dwordx4 v[54:55], v[26:29], off offset:3072
	s_nop 1
	v_add_f32_e32 v24, v24, v25
	s_nop 0
	v_pk_mul_f32 v[26:27], v[18:19], v[18:19]
	s_nop 0
	v_add_f32_e32 v24, v27, v24
	v_add_f32_e32 v24, v26, v24
	s_nop 1
	v_add_f32_dpp v24, v24, v24 quad_perm:[1,0,3,2] row_mask:0xf bank_mask:0xf
	s_nop 1
	v_add_f32_dpp v24, v24, v24 quad_perm:[2,3,0,1] row_mask:0xf bank_mask:0xf
	s_nop 1
	v_add_f32_dpp v24, v24, v24 row_half_mirror row_mask:0xf bank_mask:0xf
	s_nop 1
	v_add_f32_dpp v24, v24, v24 row_mirror row_mask:0xf bank_mask:0xf
	ds_bpermute_b32 v25, v60, v24
	s_waitcnt lgkmcnt(0)
	v_add_f32_e32 v24, v24, v25
	ds_bpermute_b32 v25, v61, v24
	s_waitcnt lgkmcnt(0)
	v_add_f32_e32 v24, v24, v25
	v_fmamk_f32 v24, v24, 0x3b800000, v216
	v_cmp_gt_f32_e64 s[52:53], s26, v24
	v_mul_f32_e32 v25, 0x4b800000, v24
	s_nop 0
	v_cndmask_b32_e64 v24, v24, v25, s[52:53]
	v_rsq_f32_e32 v24, v24
	s_nop 0
	v_mul_f32_e32 v25, 0x45800000, v24
	v_cndmask_b32_e64 v26, v24, v25, s[52:53]
	v_mov_b64_e32 v[24:25], v[134:135]
	v_mul_f32_e32 v20, v26, v20
	v_mul_f32_e32 v21, v26, v21
	v_mul_f32_e32 v19, v26, v19
	v_mul_f32_e32 v18, v26, v18
	v_mul_f32_e32 v20, v24, v20
	v_mul_f32_e32 v21, v25, v21
	v_cvt_pk_bf16_f32 v20, v20, v21
	v_mov_b64_e32 v[24:25], v[136:137]
	v_mul_f32_e32 v19, v24, v19
	v_mul_f32_e32 v18, v25, v18
	v_cvt_pk_bf16_f32 v21, v19, v18
	v_and_b32_e32 v19, 0xffff0000, v94
	global_store_dwordx2 v[22:23], v[20:21], off
	s_nop 1
	v_lshlrev_b32_e32 v18, 16, v94
	v_cndmask_b32_e64 v21, 0, v19, s[42:43]
	v_cndmask_b32_e64 v18, 0, v18, s[42:43]
	v_mul_f32_e32 v19, v21, v21
	v_fmac_f32_e32 v19, v18, v18
	s_nop 1
	v_add_f32_dpp v19, v19, v19 quad_perm:[1,0,3,2] row_mask:0xf bank_mask:0xf
	s_nop 1
	v_add_f32_dpp v19, v19, v19 quad_perm:[2,3,0,1] row_mask:0xf bank_mask:0xf
	s_nop 1
	v_add_f32_dpp v19, v19, v19 row_half_mirror row_mask:0xf bank_mask:0xf
	s_nop 1
	v_add_f32_dpp v19, v19, v19 row_mirror row_mask:0xf bank_mask:0xf
	ds_bpermute_b32 v20, v60, v19
	s_waitcnt lgkmcnt(0)
	v_add_f32_e32 v19, v19, v20
	ds_bpermute_b32 v20, v61, v19
	s_waitcnt lgkmcnt(0)
	v_add_f32_e32 v19, v19, v20
	v_fmamk_f32 v19, v19, 0x3c800000, v216
	v_cmp_gt_f32_e64 s[52:53], s26, v19
	v_mul_f32_e32 v20, 0x4b800000, v19
	s_nop 0
	v_cndmask_b32_e64 v19, v19, v20, s[52:53]
	v_rsq_f32_e32 v19, v19
	s_nop 0
	v_mul_f32_e32 v20, 0x45800000, v19
	v_cndmask_b32_e64 v20, v19, v20, s[52:53]
	v_mov_b32_e32 v19, v20
	v_pk_mul_f32 v[18:19], v[20:21], v[18:19]
	v_mov_b64_e32 v[20:21], v[138:139]
	v_pk_mul_f32 v[18:19], v[20:21], v[18:19]
	s_and_saveexec_b64 s[14:15], s[48:49]
	s_cbranch_execnz .LBB0_53
	s_or_b64 exec, exec, s[14:15]
	s_and_saveexec_b64 s[14:15], s[42:43]
	s_cbranch_execnz .LBB0_54

; __device__ __forceinline__ float bflo(unsigned w) { return __uint_as_float(w << 16); }
; __device__ __forceinline__ float bfhi(unsigned w) { return __uint_as_float(w & 0xffff0000u); }
; __device__ __forceinline__ unsigned cvt_pk_bf16(float lo, float hi) { unsigned r; asm volatile("v_cvt_pk_bf16_f32 %0, %1, %2" : "=v"(r) : "v"(lo), "v"(hi)); return r; }
; __device__ __forceinline__ void e1_row(CArgs& a, int l, int r, int lane, int dup, const E1Regs& g) {
;     ...
;       for (int t = 0; t < 3; ++t) { const int hh = 4 * t + hsub; const u32x4 w = g.hq[t];
;           float x[8] = {bflo(w.x), bfhi(w.x), bflo(w.y), bfhi(w.y), bflo(w.z), bfhi(w.z), bflo(w.w), bfhi(w.w)};
;           float ss = 0.f;
; #pragma unroll
;           for (int e = 0; e < 8; ++e) ss += x[e] * x[e];
; #pragma unroll
;           for (int m = 1; m < 16; m <<= 1) ss += __shfl_xor(ss, m);
;           const float rs = rsqrtf(ss * (1.f / 128.f) + EPS) * (hh < 8 ? QSCALE_A : 1.f);
;           const float* gg = a.in[hh < 8 ? I_AQN : I_AKN] + l * 128 + 8 * li;
;           const f32x4 ga = *(const f32x4*)gg, gb = *(const f32x4*)(gg + 4);
;           float y[8] = {x[0] * rs * ga.x, x[1] * rs * ga.y, x[2] * rs * ga.z, x[3] * rs * ga.w, x[4] * rs * gb.x, x[5] * rs * gb.y, x[6] * rs * gb.z, x[7] * rs * gb.w};
;           if (lat) {
; #pragma unroll
;               for (int e = 0; e < 8; ++e) { const float p = __shfl_xor(y[e], 4); y[e] = second ? (p * sn[e] + y[e] * cs[e]) : (y[e] * cs[e] - p * sn[e]); } }
;           u32x4 o; o.x = cvt_pk_bf16(y[0], y[1]); o.y = cvt_pk_bf16(y[2], y[3]); o.z = cvt_pk_bf16(y[4], y[5]); o.w = cvt_pk_bf16(y[6], y[7]);
;           if (hh < 10) *((u32x4*)(P + t * 512) + lane) = o; } }
.LBB0_57:
	s_or_b64 exec, exec, s[22:23]
	v_mov_b64_e32 v[52:53], v[110:111]
	v_mov_b64_e32 v[54:55], v[112:113]
	v_mov_b64_e32 v[56:57], v[114:115]
	v_mov_b64_e32 v[58:59], v[116:117]
	v_lshlrev_b32_e32 v64, 16, v14
	v_and_b32_e32 v65, 0xffff0000, v14
	v_lshlrev_b32_e32 v14, 16, v15
	v_and_b32_e32 v15, 0xffff0000, v15
	v_pk_mul_f32 v[68:69], v[64:65], v[64:65]
	v_pk_mul_f32 v[70:71], v[14:15], v[14:15]
	v_add_f32_e32 v47, v68, v69
	v_lshlrev_b32_e32 v66, 16, v16
	v_and_b32_e32 v67, 0xffff0000, v16
	v_add_f32_e32 v47, v70, v47
	v_pk_mul_f32 v[72:73], v[66:67], v[66:67]
	v_add_f32_e32 v47, v71, v47
	v_lshlrev_b32_e32 v16, 16, v17
	v_and_b32_e32 v17, 0xffff0000, v17
	v_add_f32_e32 v47, v72, v47
	v_pk_mul_f32 v[74:75], v[16:17], v[16:17]
	v_add_f32_e32 v47, v73, v47
	v_add_f32_e32 v47, v74, v47
	v_add_f32_e32 v47, v75, v47
	s_nop 1
	v_add_f32_dpp v47, v47, v47 quad_perm:[1,0,3,2] row_mask:0xf bank_mask:0xf
	s_nop 1
	v_add_f32_dpp v47, v47, v47 quad_perm:[2,3,0,1] row_mask:0xf bank_mask:0xf
	s_nop 1
	v_add_f32_dpp v47, v47, v47 row_half_mirror row_mask:0xf bank_mask:0xf
	s_nop 1
	v_add_f32_dpp v47, v47, v47 row_mirror row_mask:0xf bank_mask:0xf
	v_fmamk_f32 v47, v47, 0x3c000000, v216
	v_mul_f32_e32 v49, 0x4b800000, v47
	v_cmp_gt_f32_e64 s[48:49], s26, v47
	s_nop 1
	v_cndmask_b32_e64 v47, v47, v49, s[48:49]
	v_rsq_f32_e32 v47, v47
	s_nop 0
	v_mul_f32_e32 v49, 0x45800000, v47
	v_cndmask_b32_e64 v47, v47, v49, s[48:49]
	v_mul_f32_e32 v68, 0x3e0293ee, v47
	v_pk_mul_f32 v[64:65], v[68:69], v[64:65] op_sel_hi:[0,1]
	v_pk_mul_f32 v[14:15], v[68:69], v[14:15] op_sel_hi:[0,1]
	v_pk_mul_f32 v[66:67], v[68:69], v[66:67] op_sel_hi:[0,1]
	v_pk_mul_f32 v[16:17], v[68:69], v[16:17] op_sel_hi:[0,1]
	v_pk_mul_f32 v[52:53], v[52:53], v[64:65]
	v_pk_mul_f32 v[54:55], v[54:55], v[14:15]
	v_pk_mul_f32 v[56:57], v[56:57], v[66:67]
	v_pk_mul_f32 v[58:59], v[58:59], v[16:17]
	s_and_saveexec_b64 s[22:23], vcc
	s_cbranch_execz .LBB0_59
	ds_bpermute_b32 v14, v93, v52
	ds_bpermute_b32 v15, v93, v53
	ds_bpermute_b32 v16, v93, v54
	ds_bpermute_b32 v17, v93, v55
	ds_bpermute_b32 v64, v93, v56
	ds_bpermute_b32 v65, v93, v57
	ds_bpermute_b32 v66, v93, v58
	ds_bpermute_b32 v67, v93, v59
	s_waitcnt lgkmcnt(6)
	v_pk_mul_f32 v[14:15], v[32:33], v[14:15]
	s_waitcnt lgkmcnt(4)
	v_pk_mul_f32 v[16:17], v[30:31], v[16:17]
	s_waitcnt lgkmcnt(2)
	v_pk_mul_f32 v[64:65], v[28:29], v[64:65]
	v_cndmask_b32_e64 v15, v15, -v15, s[38:39]
	s_waitcnt lgkmcnt(0)
	v_pk_mul_f32 v[66:67], v[26:27], v[66:67]
	v_cndmask_b32_e64 v14, v14, -v14, s[38:39]
	v_cndmask_b32_e64 v17, v17, -v17, s[38:39]
	v_cndmask_b32_e64 v16, v16, -v16, s[38:39]
	v_cndmask_b32_e64 v65, v65, -v65, s[38:39]
	v_cndmask_b32_e64 v64, v64, -v64, s[38:39]
	v_cndmask_b32_e64 v66, v66, -v66, s[38:39]
	v_cndmask_b32_e64 v67, v67, -v67, s[38:39]
	v_pk_fma_f32 v[58:59], v[24:25], v[58:59], v[66:67]
	v_pk_fma_f32 v[56:57], v[22:23], v[56:57], v[64:65]
	v_pk_fma_f32 v[54:55], v[20:21], v[54:55], v[16:17]
	v_pk_fma_f32 v[52:53], v[18:19], v[52:53], v[14:15]
.LBB0_59:
	s_or_b64 exec, exec, s[22:23]
	v_ashrrev_i32_e32 v47, 31, v46
	v_lshlrev_b64 v[14:15], 13, v[46:47]
	v_lshl_add_u64 v[14:15], s[54:55], 0, v[14:15]
	v_lshl_add_u64 v[16:17], v[14:15], 0, v[0:1]
	v_cvt_pk_bf16_f32 v52, v52, v53
	v_cvt_pk_bf16_f32 v53, v54, v55
	v_cvt_pk_bf16_f32 v54, v56, v57
	v_cvt_pk_bf16_f32 v55, v58, v59
	global_store_dwordx4 v[16:17], v[52:55], off
	s_nop 1
	v_mov_b64_e32 v[52:53], v[110:111]
	v_mov_b64_e32 v[54:55], v[112:113]
	s_nop 0
	v_mov_b64_e32 v[56:57], v[114:115]
	v_mov_b64_e32 v[58:59], v[116:117]
	v_lshlrev_b32_e32 v64, 16, v10
	v_and_b32_e32 v65, 0xffff0000, v10
	v_lshlrev_b32_e32 v10, 16, v11
	v_and_b32_e32 v11, 0xffff0000, v11
	v_pk_mul_f32 v[68:69], v[64:65], v[64:65]
	v_pk_mul_f32 v[70:71], v[10:11], v[10:11]
	v_add_f32_e32 v0, v68, v69
	v_lshlrev_b32_e32 v66, 16, v12
	v_and_b32_e32 v67, 0xffff0000, v12
	v_add_f32_e32 v0, v70, v0
	v_pk_mul_f32 v[72:73], v[66:67], v[66:67]
	v_add_f32_e32 v0, v71, v0
	v_lshlrev_b32_e32 v12, 16, v13
	v_and_b32_e32 v13, 0xffff0000, v13
	v_add_f32_e32 v0, v72, v0
	v_pk_mul_f32 v[74:75], v[12:13], v[12:13]
	v_add_f32_e32 v0, v73, v0
	v_add_f32_e32 v0, v74, v0
	v_add_f32_e32 v0, v75, v0
	s_nop 1
	v_add_f32_dpp v0, v0, v0 quad_perm:[1,0,3,2] row_mask:0xf bank_mask:0xf
	s_nop 1
	v_add_f32_dpp v0, v0, v0 quad_perm:[2,3,0,1] row_mask:0xf bank_mask:0xf
	s_nop 1
	v_add_f32_dpp v0, v0, v0 row_half_mirror row_mask:0xf bank_mask:0xf
	s_nop 1
	v_add_f32_dpp v0, v0, v0 row_mirror row_mask:0xf bank_mask:0xf
	v_fmamk_f32 v0, v0, 0x3c000000, v216
	v_mul_f32_e32 v47, 0x4b800000, v0
	v_cmp_gt_f32_e64 s[48:49], s26, v0
	s_nop 1
	v_cndmask_b32_e64 v0, v0, v47, s[48:49]
	v_rsq_f32_e32 v0, v0
	s_nop 0
	v_mul_f32_e32 v47, 0x45800000, v0
	v_cndmask_b32_e64 v0, v0, v47, s[48:49]
	v_mul_f32_e32 v0, 0x3e0293ee, v0
	v_pk_mul_f32 v[64:65], v[0:1], v[64:65] op_sel_hi:[0,1]
	v_pk_mul_f32 v[68:69], v[0:1], v[10:11] op_sel_hi:[0,1]
	v_pk_mul_f32 v[66:67], v[0:1], v[66:67] op_sel_hi:[0,1]
	v_pk_mul_f32 v[70:71], v[0:1], v[12:13] op_sel_hi:[0,1]
	v_pk_mul_f32 v[10:11], v[52:53], v[64:65]
	v_pk_mul_f32 v[12:13], v[54:55], v[68:69]
	v_pk_mul_f32 v[52:53], v[56:57], v[66:67]
	v_pk_mul_f32 v[54:55], v[58:59], v[70:71]
	s_and_saveexec_b64 s[22:23], vcc
	s_cbranch_execz .LBB0_61
	ds_bpermute_b32 v56, v93, v10
	ds_bpermute_b32 v57, v93, v11
	ds_bpermute_b32 v58, v93, v12
	ds_bpermute_b32 v59, v93, v13
	ds_bpermute_b32 v64, v93, v52
	ds_bpermute_b32 v65, v93, v53
	ds_bpermute_b32 v66, v93, v54
	ds_bpermute_b32 v67, v93, v55
	s_waitcnt lgkmcnt(6)
	v_pk_mul_f32 v[56:57], v[32:33], v[56:57]
	s_waitcnt lgkmcnt(4)
	v_pk_mul_f32 v[58:59], v[30:31], v[58:59]
	s_waitcnt lgkmcnt(2)
	v_pk_mul_f32 v[64:65], v[28:29], v[64:65]
	v_cndmask_b32_e64 v57, v57, -v57, s[38:39]
	s_waitcnt lgkmcnt(0)
	v_pk_mul_f32 v[66:67], v[26:27], v[66:67]
	v_cndmask_b32_e64 v56, v56, -v56, s[38:39]
	v_cndmask_b32_e64 v59, v59, -v59, s[38:39]
	v_cndmask_b32_e64 v58, v58, -v58, s[38:39]
	v_cndmask_b32_e64 v65, v65, -v65, s[38:39]
	v_cndmask_b32_e64 v64, v64, -v64, s[38:39]
	v_cndmask_b32_e64 v66, v66, -v66, s[38:39]
	v_cndmask_b32_e64 v67, v67, -v67, s[38:39]
	v_pk_fma_f32 v[54:55], v[24:25], v[54:55], v[66:67]
	v_pk_fma_f32 v[52:53], v[22:23], v[52:53], v[64:65]
	v_pk_fma_f32 v[12:13], v[20:21], v[12:13], v[58:59]
	v_pk_fma_f32 v[10:11], v[18:19], v[10:11], v[56:57]
; __device__ __forceinline__ float bflo(unsigned w) { return __uint_as_float(w << 16); }
; __device__ __forceinline__ float bfhi(unsigned w) { return __uint_as_float(w & 0xffff0000u); }
; __device__ __forceinline__ unsigned cvt_pk_bf16(float lo, float hi) { unsigned r; asm volatile("v_cvt_pk_bf16_f32 %0, %1, %2" : "=v"(r) : "v"(lo), "v"(hi)); return r; }
; __device__ __forceinline__ void e1_row(CArgs& a, int l, int r, int lane, int dup, const E1Regs& g) {
;     ...
;       for (int t = 0; t < 3; ++t) { const int hh = 4 * t + hsub; const u32x4 w = g.hq[t];
;           float x[8] = {bflo(w.x), bfhi(w.x), bflo(w.y), bfhi(w.y), bflo(w.z), bfhi(w.z), bflo(w.w), bfhi(w.w)};
;           float ss = 0.f;
; #pragma unroll
;           for (int e = 0; e < 8; ++e) ss += x[e] * x[e];
; #pragma unroll
;           for (int m = 1; m < 16; m <<= 1) ss += __shfl_xor(ss, m);
;           const float rs = rsqrtf(ss * (1.f / 128.f) + EPS) * (hh < 8 ? QSCALE_A : 1.f);
;           const float* gg = a.in[hh < 8 ? I_AQN : I_AKN] + l * 128 + 8 * li;
;           const f32x4 ga = *(const f32x4*)gg, gb = *(const f32x4*)(gg + 4);
;           float y[8] = {x[0] * rs * ga.x, x[1] * rs * ga.y, x[2] * rs * ga.z, x[3] * rs * ga.w, x[4] * rs * gb.x, x[5] * rs * gb.y, x[6] * rs * gb.z, x[7] * rs * gb.w};
;           if (lat) {
; #pragma unroll
;               for (int e = 0; e < 8; ++e) { const float p = __shfl_xor(y[e], 4); y[e] = second ? (p * sn[e] + y[e] * cs[e]) : (y[e] * cs[e] - p * sn[e]); } }
;           u32x4 o; o.x = cvt_pk_bf16(y[0], y[1]); o.y = cvt_pk_bf16(y[2], y[3]); o.z = cvt_pk_bf16(y[4], y[5]); o.w = cvt_pk_bf16(y[6], y[7]);
;           if (hh < 10) *((u32x4*)(P + t * 512) + lane) = o; } }
.LBB0_61:
	s_or_b64 exec, exec, s[22:23]
	v_cvt_pk_bf16_f32 v10, v10, v11
	v_cvt_pk_bf16_f32 v11, v12, v13
	v_cvt_pk_bf16_f32 v12, v52, v53
	v_cvt_pk_bf16_f32 v13, v54, v55
	global_store_dwordx4 v[16:17], v[10:13], off offset:1024
	s_nop 1
	v_mov_b64_e32 v[10:11], v[118:119]
	v_mov_b64_e32 v[12:13], v[120:121]
	s_nop 0
	v_mov_b64_e32 v[52:53], v[122:123]
	v_mov_b64_e32 v[54:55], v[124:125]
	v_lshlrev_b32_e32 v56, 16, v6
	v_and_b32_e32 v57, 0xffff0000, v6
	v_lshlrev_b32_e32 v6, 16, v7
	v_and_b32_e32 v7, 0xffff0000, v7
	v_pk_mul_f32 v[64:65], v[56:57], v[56:57]
	v_pk_mul_f32 v[66:67], v[6:7], v[6:7]
	v_add_f32_e32 v0, v64, v65
	v_lshlrev_b32_e32 v58, 16, v8
	v_and_b32_e32 v59, 0xffff0000, v8
	v_add_f32_e32 v0, v66, v0
	v_pk_mul_f32 v[68:69], v[58:59], v[58:59]
	v_add_f32_e32 v0, v67, v0
	v_lshlrev_b32_e32 v8, 16, v9
	v_and_b32_e32 v9, 0xffff0000, v9
	v_add_f32_e32 v0, v68, v0
	v_pk_mul_f32 v[70:71], v[8:9], v[8:9]
	v_add_f32_e32 v0, v69, v0
	v_add_f32_e32 v0, v70, v0
	v_add_f32_e32 v0, v71, v0
	s_nop 1
	v_add_f32_dpp v0, v0, v0 quad_perm:[1,0,3,2] row_mask:0xf bank_mask:0xf
	s_nop 1
	v_add_f32_dpp v0, v0, v0 quad_perm:[2,3,0,1] row_mask:0xf bank_mask:0xf
	s_nop 1
	v_add_f32_dpp v0, v0, v0 row_half_mirror row_mask:0xf bank_mask:0xf
	s_nop 1
	v_add_f32_dpp v0, v0, v0 row_mirror row_mask:0xf bank_mask:0xf
	v_fmamk_f32 v0, v0, 0x3c000000, v216
	v_mul_f32_e32 v47, 0x4b800000, v0
	v_cmp_gt_f32_e64 s[48:49], s26, v0
	s_nop 1
	v_cndmask_b32_e64 v0, v0, v47, s[48:49]
	v_rsq_f32_e32 v0, v0
	s_nop 0
	v_mul_f32_e32 v47, 0x45800000, v0
	v_cndmask_b32_e64 v0, v0, v47, s[48:49]
	v_pk_mul_f32 v[56:57], v[0:1], v[56:57] op_sel_hi:[0,1]
	v_pk_mul_f32 v[64:65], v[0:1], v[6:7] op_sel_hi:[0,1]
	v_pk_mul_f32 v[58:59], v[0:1], v[58:59] op_sel_hi:[0,1]
	v_pk_mul_f32 v[66:67], v[0:1], v[8:9] op_sel_hi:[0,1]
	v_pk_mul_f32 v[6:7], v[10:11], v[56:57]
	v_pk_mul_f32 v[8:9], v[12:13], v[64:65]
	v_pk_mul_f32 v[10:11], v[52:53], v[58:59]
	v_pk_mul_f32 v[12:13], v[54:55], v[66:67]
	s_and_saveexec_b64 s[22:23], vcc
	s_cbranch_execz .LBB0_63
	ds_bpermute_b32 v52, v93, v6
	ds_bpermute_b32 v53, v93, v7
	s_waitcnt lgkmcnt(0)
	v_pk_mul_f32 v[32:33], v[32:33], v[52:53]
	ds_bpermute_b32 v52, v93, v8
	ds_bpermute_b32 v53, v93, v9
	v_cndmask_b32_e64 v33, v33, -v33, s[38:39]
	v_cndmask_b32_e64 v32, v32, -v32, s[38:39]
	v_pk_fma_f32 v[6:7], v[18:19], v[6:7], v[32:33]
	s_waitcnt lgkmcnt(0)
	v_pk_mul_f32 v[30:31], v[30:31], v[52:53]
	ds_bpermute_b32 v52, v93, v10
	ds_bpermute_b32 v53, v93, v11
	v_cndmask_b32_e64 v31, v31, -v31, s[38:39]
	v_cndmask_b32_e64 v30, v30, -v30, s[38:39]
	v_pk_fma_f32 v[8:9], v[20:21], v[8:9], v[30:31]
	s_waitcnt lgkmcnt(0)
	v_pk_mul_f32 v[28:29], v[28:29], v[52:53]
	ds_bpermute_b32 v52, v93, v12
	ds_bpermute_b32 v53, v93, v13
	v_cndmask_b32_e64 v29, v29, -v29, s[38:39]
	v_cndmask_b32_e64 v28, v28, -v28, s[38:39]
	v_pk_fma_f32 v[10:11], v[22:23], v[10:11], v[28:29]
	s_waitcnt lgkmcnt(0)
	v_pk_mul_f32 v[26:27], v[26:27], v[52:53]
	s_nop 0
	v_cndmask_b32_e64 v26, v26, -v26, s[38:39]
	v_cndmask_b32_e64 v27, v27, -v27, s[38:39]
	v_pk_fma_f32 v[12:13], v[24:25], v[12:13], v[26:27]

; __device__ __forceinline__ void rope64(float& y0, float& y1, int lane, int prow, int pcol) {
;     const int l = lane & 31;
;     const float pos = (float)(l < 16 ? prow : pcol);
;     const int i0 = (2 * l) & 15;
;     const float f0 = __builtin_amdgcn_exp2f(-(float)i0 * (13.287712379549449f / 16.f)), f1 = __builtin_amdgcn_exp2f(-(float)(i0 + 1) * (13.287712379549449f / 16.f));
;     const float a0 = pos * f0, a1 = pos * f1;
;     const float c0 = __cosf(a0), s0 = __sinf(a0), c1 = __cosf(a1), s1 = __sinf(a1);
;     const float p0 = __shfl_xor(y0, 8), p1 = __shfl_xor(y1, 8);
;     if (((l >> 3) & 1) == 0) { y0 = y0 * c0 - p0 * s0; y1 = y1 * c1 - p1 * s1; }
; __device__ __forceinline__ void e1_row(CArgs& a, int l, int r, int lane, int dup, const E1Regs& g) {
;     ...
;     { const u32x4 w = g.cqw;
;         float x[8] = {bflo(w.x), bfhi(w.x), bflo(w.y), bfhi(w.y), bflo(w.z), bfhi(w.z), bflo(w.w), bfhi(w.w)};
;         float ss = 0.f;
; #pragma unroll
;         for (int e = 0; e < 8; ++e) ss += x[e] * x[e];
;         const float rs = rsqrtf(wave_sum(ss) * (1.f / 512.f) + EPS);
;         const float* gg = a.in[I_BQLN] + l * 512 + 8 * lane;
;         u32x4 o; o.x = cvt_pk_bf16(x[0] * rs * gg[0], x[1] * rs * gg[1]); o.y = cvt_pk_bf16(x[2] * rs * gg[2], x[3] * rs * gg[3]);
;         o.z = cvt_pk_bf16(x[4] * rs * gg[4], x[5] * rs * gg[5]); o.w = cvt_pk_bf16(x[6] * rs * gg[6], x[7] * rs * gg[7]); *((u32x4*)(P + C_BCQ) + lane) = o;
;     }
;     { const u32x2 w = g.ckw;
;         float x[4] = {bflo(w.x), bfhi(w.x), bflo(w.y), bfhi(w.y)};
;         const float rs = rsqrtf(wave_sum(x[0] * x[0] + x[1] * x[1] + x[2] * x[2] + x[3] * x[3]) * (1.f / 256.f) + EPS);
;         const float* gg = a.in[I_BKVLN] + l * 256 + 4 * lane;
;         u32x2 o; o.x = cvt_pk_bf16(x[0] * rs * gg[0], x[1] * rs * gg[1]); o.y = cvt_pk_bf16(x[2] * rs * gg[2], x[3] * rs * gg[3]); *((u32x2*)(P + C_BCKV) + lane) = o;
;     }
;     { const unsigned w = g.krw;
;         float x0 = lane < 32 ? bflo(w) : 0.f, x1 = lane < 32 ? bfhi(w) : 0.f;
;         const float rs = rsqrtf(wave_sum(x0 * x0 + x1 * x1) * (1.f / 64.f) + EPS);
;         const float* gg = a.in[I_BKRN] + l * 64 + 2 * (lane & 31);
;         float y0 = x0 * rs * gg[0], y1 = x1 * rs * gg[1];
;         if (lat) rope64(y0, y1, lane, prow, pcol);
;         if (lane < 32) *((unsigned*)(P + C_BKR) + lane) = cvt_pk_bf16(y0, y1);
;     }
.LBB0_65:
	s_or_b64 exec, exec, s[14:15]
	s_nop 0
	v_and_b32_e32 v8, 0xffff0000, v2
	v_lshlrev_b32_e32 v0, 16, v2
	v_mul_f32_e32 v11, v8, v8
	v_lshlrev_b32_e32 v9, 16, v3
	v_fmac_f32_e32 v11, v0, v0
	v_and_b32_e32 v10, 0xffff0000, v3
	v_fmac_f32_e32 v11, v9, v9
	v_and_b32_e32 v6, 0xffff0000, v4
	v_lshlrev_b32_e32 v7, 16, v4
	v_fmac_f32_e32 v11, v10, v10
	v_pk_mul_f32 v[2:3], v[6:7], v[6:7]
	v_mov_b32_e32 v49, v1
	v_add_f32_e32 v3, v3, v11
	v_add_f32_e32 v11, v2, v3
	v_and_b32_e32 v2, 0xffff0000, v5
	v_lshlrev_b32_e32 v3, 16, v5
	v_pk_mul_f32 v[4:5], v[2:3], v[2:3]
	s_nop 0
	v_add_f32_e32 v5, v5, v11
	v_add_f32_e32 v4, v4, v5
	s_nop 1
	v_add_f32_dpp v4, v4, v4 quad_perm:[1,0,3,2] row_mask:0xf bank_mask:0xf
	s_nop 1
	v_add_f32_dpp v4, v4, v4 quad_perm:[2,3,0,1] row_mask:0xf bank_mask:0xf
	s_nop 1
	v_add_f32_dpp v4, v4, v4 row_half_mirror row_mask:0xf bank_mask:0xf
	s_nop 1
	v_add_f32_dpp v4, v4, v4 row_mirror row_mask:0xf bank_mask:0xf
	ds_bpermute_b32 v5, v60, v4
	s_waitcnt lgkmcnt(0)
	v_add_f32_e32 v4, v4, v5
	ds_bpermute_b32 v5, v61, v4
	s_waitcnt lgkmcnt(0)
	v_add_f32_e32 v4, v4, v5
	v_fmamk_f32 v4, v4, 0x3b000000, v216
	v_cmp_gt_f32_e64 s[48:49], s26, v4
	v_mul_f32_e32 v5, 0x4b800000, v4
	s_nop 0
	v_cndmask_b32_e64 v4, v4, v5, s[48:49]
	v_rsq_f32_e32 v4, v4
	s_nop 0
	v_mul_f32_e32 v5, 0x45800000, v4
	v_cndmask_b32_e64 v11, v4, v5, s[48:49]
	v_mov_b64_e32 v[4:5], v[126:127]
	v_mul_f32_e32 v0, v11, v0
	v_mul_f32_e32 v6, v11, v6
	v_mul_f32_e32 v2, v11, v2
	v_mul_f32_e32 v0, v4, v0
	v_mul_f32_e32 v4, v11, v8
	v_mul_f32_e32 v4, v5, v4
	v_cvt_pk_bf16_f32 v4, v0, v4
	v_mul_f32_e32 v0, v11, v9
	v_mov_b64_e32 v[8:9], v[128:129]
	v_mul_f32_e32 v5, v11, v10
	v_mul_f32_e32 v5, v9, v5
	v_mul_f32_e32 v0, v8, v0
	v_cvt_pk_bf16_f32 v5, v0, v5
	v_mov_b64_e32 v[8:9], v[130:131]
	v_mul_f32_e32 v0, v11, v7
	v_mul_f32_e32 v6, v9, v6
	v_mul_f32_e32 v0, v8, v0
	v_cvt_pk_bf16_f32 v6, v0, v6
	v_mov_b64_e32 v[8:9], v[132:133]
	v_mul_f32_e32 v0, v11, v3
	v_lshlrev_b32_e32 v3, 16, v51
	v_mul_f32_e32 v0, v0, v8
	v_mul_f32_e32 v2, v2, v9
	v_cvt_pk_bf16_f32 v7, v0, v2
	global_store_dwordx4 v[16:17], v[4:7], off offset:3072
	s_nop 1
	v_and_b32_e32 v2, 0xffff0000, v51
	v_pk_mul_f32 v[8:9], v[2:3], v[2:3]
	v_lshlrev_b32_e32 v4, 16, v50
	v_and_b32_e32 v5, 0xffff0000, v50
	v_pk_mul_f32 v[6:7], v[4:5], v[4:5]
	s_nop 0
	v_add_f32_e32 v0, v6, v7
	v_add_f32_e32 v0, v9, v0
	v_add_f32_e32 v0, v8, v0
	s_nop 1
	v_add_f32_dpp v0, v0, v0 quad_perm:[1,0,3,2] row_mask:0xf bank_mask:0xf
	s_nop 1
	v_add_f32_dpp v0, v0, v0 quad_perm:[2,3,0,1] row_mask:0xf bank_mask:0xf
	s_nop 1
	v_add_f32_dpp v0, v0, v0 row_half_mirror row_mask:0xf bank_mask:0xf
	s_nop 1
	v_add_f32_dpp v0, v0, v0 row_mirror row_mask:0xf bank_mask:0xf
	ds_bpermute_b32 v6, v60, v0
	s_waitcnt lgkmcnt(0)
	v_add_f32_e32 v0, v0, v6
	ds_bpermute_b32 v6, v61, v0
	s_waitcnt lgkmcnt(0)
	v_add_f32_e32 v0, v0, v6
	v_fmamk_f32 v0, v0, 0x3b800000, v216
	v_cmp_gt_f32_e64 s[48:49], s26, v0
	v_mul_f32_e32 v6, 0x4b800000, v0
	s_nop 0
	v_cndmask_b32_e64 v0, v0, v6, s[48:49]
	v_rsq_f32_e32 v0, v0
	s_nop 0
	v_mul_f32_e32 v6, 0x45800000, v0
	v_cndmask_b32_e64 v0, v0, v6, s[48:49]
	v_mov_b64_e32 v[6:7], v[134:135]
	v_mul_f32_e32 v4, v0, v4
	v_mul_f32_e32 v5, v0, v5
	v_mul_f32_e32 v3, v0, v3
	v_mul_f32_e32 v0, v0, v2
	v_mul_f32_e32 v4, v6, v4
	v_mul_f32_e32 v5, v7, v5
	v_cvt_pk_bf16_f32 v4, v4, v5
	v_mov_b64_e32 v[6:7], v[136:137]
	v_mul_f32_e32 v3, v6, v3
	v_mul_f32_e32 v0, v7, v0
	v_cvt_pk_bf16_f32 v5, v3, v0
	v_lshl_add_u64 v[2:3], v[14:15], 0, v[48:49]
	v_add_co_u32_e64 v2, s[48:49], s10, v2
	v_lshlrev_b32_e32 v0, 16, v90
	s_nop 0
	v_addc_co_u32_e64 v3, s[48:49], 0, v3, s[48:49]
	global_store_dwordx2 v[2:3], v[4:5], off
	s_nop 1
	v_and_b32_e32 v3, 0xffff0000, v90
	v_cndmask_b32_e64 v5, 0, v3, s[42:43]
	v_cndmask_b32_e64 v2, 0, v0, s[42:43]
	v_mul_f32_e32 v0, v5, v5
	v_fmac_f32_e32 v0, v2, v2
	s_nop 1
	v_add_f32_dpp v0, v0, v0 quad_perm:[1,0,3,2] row_mask:0xf bank_mask:0xf
	s_nop 1
	v_add_f32_dpp v0, v0, v0 quad_perm:[2,3,0,1] row_mask:0xf bank_mask:0xf
	s_nop 1
	v_add_f32_dpp v0, v0, v0 row_half_mirror row_mask:0xf bank_mask:0xf
	s_nop 1
	v_add_f32_dpp v0, v0, v0 row_mirror row_mask:0xf bank_mask:0xf
	ds_bpermute_b32 v3, v60, v0
	s_waitcnt lgkmcnt(0)
	v_add_f32_e32 v0, v0, v3
	ds_bpermute_b32 v3, v61, v0
	s_waitcnt lgkmcnt(0)
	v_add_f32_e32 v0, v0, v3
	v_fmamk_f32 v0, v0, 0x3c800000, v216
	v_cmp_gt_f32_e64 s[48:49], s26, v0
	v_mul_f32_e32 v3, 0x4b800000, v0
	s_nop 0
	v_cndmask_b32_e64 v0, v0, v3, s[48:49]
	v_rsq_f32_e32 v0, v0
	s_nop 0
	v_mul_f32_e32 v3, 0x45800000, v0
	v_cndmask_b32_e64 v4, v0, v3, s[48:49]
	v_mov_b32_e32 v3, v4
	v_pk_mul_f32 v[2:3], v[4:5], v[2:3]
	v_mov_b64_e32 v[4:5], v[138:139]
	v_pk_mul_f32 v[2:3], v[4:5], v[2:3]
	s_and_saveexec_b64 s[14:15], vcc
	s_cbranch_execz .LBB0_67
	v_cndmask_b32_e64 v0, v63, v62, s[44:45]
	v_cvt_f32_i32_e32 v0, v0
	ds_bpermute_b32 v4, v45, v2
	v_mul_f32_e32 v5, v88, v0
	v_mul_f32_e32 v0, v89, v0
	v_mul_f32_e32 v8, 0.15915494, v5
	v_mul_f32_e32 v0, 0.15915494, v0
	ds_bpermute_b32 v5, v45, v3
	v_sin_f32_e32 v6, v8
	v_sin_f32_e32 v7, v0
	v_cos_f32_e32 v8, v8
	v_cos_f32_e32 v9, v0
	s_waitcnt lgkmcnt(0)
	v_pk_mul_f32 v[4:5], v[6:7], v[4:5]
	s_nop 0
	v_cndmask_b32_e64 v5, v5, -v5, s[46:47]
	v_cndmask_b32_e64 v4, v4, -v4, s[46:47]
	v_pk_fma_f32 v[2:3], v[8:9], v[2:3], v[4:5]

; __device__ __forceinline__ unsigned cvt_pk_bf16(float lo, float hi) { unsigned r; asm volatile("v_cvt_pk_bf16_f32 %0, %1, %2" : "=v"(r) : "v"(lo), "v"(hi)); return r; }
; #define E2_UNPK(wv_, arr_) float arr_[8] = {bflo(wv_[0]), bfhi(wv_[0]), bflo(wv_[1]), bfhi(wv_[1]), bflo(wv_[2]), bfhi(wv_[2]), bflo(wv_[3]), bfhi(wv_[3])}
; __device__ __forceinline__ void e2_row(CArgs& a, int l, int r, int lane, int dup, const E2Regs& g) {
;     ...
;     { E2_UNPK(g.kn, x); float ss = 0.f;
; #pragma unroll
;       for (int e = 0; e < 8; ++e) ss += x[e] * x[e];
; #pragma unroll
;       for (int m = 1; m < 16; m <<= 1) ss += __shfl_xor(ss, m);
;       const float rs = rsqrtf(ss * (1.f / 128.f) + EPS);
;       const float* gg = a.in[I_BKNN] + l * 128 + 8 * li; const f32x4 ga = *(const f32x4*)gg, gb = *(const f32x4*)(gg + 4);
;       u32x4 o; o.x = cvt_pk_bf16(x[0] * rs * ga.x, x[1] * rs * ga.y); o.y = cvt_pk_bf16(x[2] * rs * ga.z, x[3] * rs * ga.w);
;       o.z = cvt_pk_bf16(x[4] * rs * gb.x, x[5] * rs * gb.y); o.w = cvt_pk_bf16(x[6] * rs * gb.z, x[7] * rs * gb.w);
;       *(u32x4*)(KB + h16 * 192 + 8 * li) = o; }
.LBB0_168:
	s_or_b64 exec, exec, s[14:15]
	v_and_b32_e32 v21, 0xffff0000, v2
	v_lshlrev_b32_e32 v20, 16, v2
	v_mul_f32_e32 v6, v21, v21
	v_and_b32_e32 v12, 0xffff0000, v3
	v_lshlrev_b32_e32 v13, 16, v3
	v_fmac_f32_e32 v6, v20, v20
	v_pk_mul_f32 v[2:3], v[12:13], v[12:13]
	v_and_b32_e32 v16, 0xffff0000, v4
	v_add_f32_e32 v3, v3, v6
	v_lshlrev_b32_e32 v17, 16, v4
	v_add_f32_e32 v6, v2, v3
	v_pk_mul_f32 v[2:3], v[16:17], v[16:17]
	v_and_b32_e32 v18, 0xffff0000, v5
	v_add_f32_e32 v3, v3, v6
	v_lshlrev_b32_e32 v19, 16, v5
	v_add_f32_e32 v4, v2, v3
	v_pk_mul_f32 v[2:3], v[18:19], v[18:19]
	s_nop 0
	v_add_f32_e32 v3, v3, v4
	v_mov_b64_e32 v[4:5], v[114:115]
	v_mov_b64_e32 v[6:7], v[116:117]
	v_mov_b64_e32 v[8:9], v[110:111]
	v_mov_b64_e32 v[10:11], v[112:113]
	v_add_f32_e32 v2, v2, v3
	s_nop 1
	v_add_f32_dpp v2, v2, v2 quad_perm:[1,0,3,2] row_mask:0xf bank_mask:0xf
	s_nop 1
	v_add_f32_dpp v2, v2, v2 quad_perm:[2,3,0,1] row_mask:0xf bank_mask:0xf
	s_nop 1
	v_add_f32_dpp v2, v2, v2 row_half_mirror row_mask:0xf bank_mask:0xf
	s_nop 1
	v_add_f32_dpp v2, v2, v2 row_mirror row_mask:0xf bank_mask:0xf
	v_fmamk_f32 v2, v2, 0x3c000000, v216
	v_cmp_gt_f32_e32 vcc, s26, v2
	v_mul_f32_e32 v3, 0x4b800000, v2
	s_nop 0
	v_cndmask_b32_e32 v2, v2, v3, vcc
	v_rsq_f32_e32 v2, v2
	s_nop 0
	v_mul_f32_e32 v3, 0x45800000, v2
	v_cndmask_b32_e32 v22, v2, v3, vcc
	v_mul_f32_e32 v2, v22, v20
	v_mul_f32_e32 v3, v22, v21
	v_mul_f32_e32 v2, v8, v2
	v_mul_f32_e32 v3, v9, v3
	v_cvt_pk_bf16_f32 v2, v2, v3
	v_mul_f32_e32 v3, v22, v13
	v_mul_f32_e32 v8, v22, v12
	v_mul_f32_e32 v3, v10, v3
	v_mul_f32_e32 v8, v11, v8
	v_cvt_pk_bf16_f32 v3, v3, v8
	v_mul_f32_e32 v8, v22, v17
	v_mul_f32_e32 v4, v4, v8
	v_mul_f32_e32 v8, v22, v16
	v_mul_f32_e32 v5, v5, v8
	v_cvt_pk_bf16_f32 v4, v4, v5
	v_mul_f32_e32 v5, v22, v19
	v_mul_f32_e32 v5, v6, v5
	v_mul_f32_e32 v6, v22, v18
	v_mul_f32_e32 v6, v7, v6
	v_cvt_pk_bf16_f32 v5, v5, v6
	v_add_co_u32_e32 v6, vcc, 0x24900000, v14
	s_nop 1
	v_addc_co_u32_e32 v7, vcc, 0, v15, vcc
	global_store_dwordx4 v[6:7], v[2:5], off
	s_nop 1

; __device__ __forceinline__ unsigned cvt_pk_bf16(float lo, float hi) { unsigned r; asm volatile("v_cvt_pk_bf16_f32 %0, %1, %2" : "=v"(r) : "v"(lo), "v"(hi)); return r; }
; __device__ __forceinline__ void e2_row(CArgs& a, int l, int r, int lane, int dup, const E2Regs& g) {
;     bf16_t* Q = dup ? (bf16_t*)((float*)a.out + (10u << 20)) + (size_t)r * 768 : (bf16_t*)(a.ws + WS_QB) + (size_t)r * 768;
;     bf16_t* KB = dup ? (bf16_t*)((float*)a.out + (18u << 20)) + (size_t)r * 768 : (bf16_t*)(a.ws + WS_KB) + (size_t)r * 768;
;     const int i = r % TOK; const bool lat = i >= CTXL; const int n = i - CTXL, prow = n >> 6, pcol = n & 63;
;     const int h16 = lane >> 4, li = lane & 15, h8 = (lane >> 3) & 3, li8 = lane & 7;
;     ...
;     { E2_UNPK(g.qn, x); float ss = 0.f;
; #pragma unroll
;       for (int e = 0; e < 8; ++e) ss += x[e] * x[e];
; #pragma unroll
;       for (int m = 1; m < 16; m <<= 1) ss += __shfl_xor(ss, m);
;       const float rs = rsqrtf(ss * (1.f / 128.f) + EPS) * QSCALE_B;
;       const float* gg = a.in[I_BQNN] + l * 128 + 8 * li; const f32x4 ga = *(const f32x4*)gg, gb = *(const f32x4*)(gg + 4);
;       u32x4 o; o.x = cvt_pk_bf16(x[0] * rs * ga.x, x[1] * rs * ga.y); o.y = cvt_pk_bf16(x[2] * rs * ga.z, x[3] * rs * ga.w);
;       o.z = cvt_pk_bf16(x[4] * rs * gb.x, x[5] * rs * gb.y); o.w = cvt_pk_bf16(x[6] * rs * gb.z, x[7] * rs * gb.w);
;       *(u32x4*)(Q + h16 * 192 + 8 * li) = o; }
;     { E2_UNPK(g.qr, x); float ss = 0.f;
; #pragma unroll
;       for (int e = 0; e < 8; ++e) ss += x[e] * x[e];
; #pragma unroll
;       for (int m = 1; m < 8; m <<= 1) ss += __shfl_xor(ss, m);
;       const float rs = rsqrtf(ss * (1.f / 64.f) + EPS) * QSCALE_B;
;       const float* gg = a.in[I_BQRN] + l * 64 + 8 * li8; const f32x4 ga = *(const f32x4*)gg, gb = *(const f32x4*)(gg + 4);
;       float y[8] = {x[0] * rs * ga.x, x[1] * rs * ga.y, x[2] * rs * ga.z, x[3] * rs * ga.w, x[4] * rs * gb.x, x[5] * rs * gb.y, x[6] * rs * gb.z, x[7] * rs * gb.w};
;       if (lat) { const float pos = (float)(li8 < 4 ? prow : pcol); const bool second = ((li8 >> 1) & 1) != 0;
; #pragma unroll
;           for (int e = 0; e < 8; ++e) { const float ang = pos * __builtin_amdgcn_exp2f(-(float)(8 * (li8 & 1) + e) * (13.287712379549449f / 16.f));
;               const float c = __cosf(ang), sn = __sinf(ang), p = __shfl_xor(y[e], 2); y[e] = second ? (p * sn + y[e] * c) : (y[e] * c - p * sn); } }
.LBB0_170:
	v_lshl_add_u64 v[60:61], s[56:57], 0, v[48:49]
	v_add_co_u32_e32 v64, vcc, 0x20d00000, v60
	v_lshl_add_u64 v[62:63], s[56:57], 0, v[46:47]
	s_nop 0
	v_addc_co_u32_e32 v65, vcc, 0, v61, vcc
	global_load_dwordx4 v[30:33], v[64:65], off
	v_add_co_u32_e32 v2, vcc, 0x20d00000, v62
	v_add_u32_e32 v82, s33, v80
	s_nop 0
	v_addc_co_u32_e32 v3, vcc, 0, v63, vcc
	s_movk_i32 s4, 0x4400
	global_load_dwordx4 v[26:29], v[2:3], off offset:256
	v_lshl_add_u64 v[2:3], s[56:57], 0, v[44:45]
	v_cmp_gt_i32_e64 s[44:45], s4, v82
	global_load_dwordx4 v[18:21], v[2:3], off
	v_lshl_add_u64 v[2:3], s[56:57], 0, v[42:43]
	global_load_dwordx4 v[22:25], v[2:3], off
	v_cndmask_b32_e64 v2, v80, v82, s[44:45]
	v_ashrrev_i32_e32 v3, 31, v2
	v_mov_b64_e32 v[4:5], s[12:13]
	s_movk_i32 s4, 0x600
	v_mad_i64_i32 v[4:5], s[4:5], v2, s4, v[4:5]
	v_lshlrev_b64 v[6:7], 11, v[2:3]
	v_lshlrev_b64 v[2:3], 13, v[2:3]
	v_lshl_add_u64 v[8:9], s[56:57], 0, v[2:3]
	v_lshl_add_u64 v[2:3], v[4:5], 0, v[0:1]
	v_mov_b32_e32 v55, v1
	v_lshl_add_u64 v[2:3], v[2:3], 0, v[54:55]
	v_mov_b32_e32 v57, v1
	v_mul_hi_i32 v55, v80, s94
	global_load_dwordx4 v[14:17], v[2:3], off
	v_lshl_add_u64 v[2:3], v[4:5], 0, v[56:57]
	v_lshrrev_b32_e32 v57, 31, v55
	v_ashrrev_i32_e32 v55, 11, v55
	v_add_u32_e32 v55, v55, v57
	v_mul_i32_i24_e32 v55, 0x1100, v55
	v_sub_u32_e32 v83, v80, v55
	v_mov_b32_e32 v59, v1
	v_lshl_add_u64 v[2:3], v[2:3], 0, v[58:59]
	global_load_dwordx4 v[10:13], v[2:3], off offset:256
	v_lshl_add_u64 v[2:3], v[34:35], 0, v[6:7]
	v_lshl_add_u64 v[6:7], v[8:9], 0, v[58:59]
	s_mov_b32 s4, 0x18501000
	v_add_co_u32_e32 v6, vcc, s4, v6
	global_load_dwordx4 v[2:5], v[2:3], off
	s_nop 0
	v_addc_co_u32_e32 v7, vcc, 0, v7, vcc
	global_load_dwordx4 v[6:9], v[6:7], off offset:512
	v_cmp_lt_i32_e32 vcc, s78, v83
	s_waitcnt vmcnt(0)
	v_and_b32_e32 v84, 0xffff0000, v30
	v_lshlrev_b32_e32 v86, 16, v30
	v_mul_f32_e32 v55, v84, v84
	v_and_b32_e32 v70, 0xffff0000, v31
	v_lshlrev_b32_e32 v71, 16, v31
	v_fmac_f32_e32 v55, v86, v86
	v_pk_mul_f32 v[30:31], v[70:71], v[70:71]
	v_and_b32_e32 v68, 0xffff0000, v32
	v_add_f32_e32 v31, v31, v55
	v_lshlrev_b32_e32 v69, 16, v32
	v_add_f32_e32 v55, v30, v31
	v_pk_mul_f32 v[30:31], v[68:69], v[68:69]
	v_and_b32_e32 v66, 0xffff0000, v33
	v_add_f32_e32 v31, v31, v55
	v_lshlrev_b32_e32 v67, 16, v33
	v_add_f32_e32 v32, v30, v31
	v_pk_mul_f32 v[30:31], v[66:67], v[66:67]
	s_nop 0
	v_add_f32_e32 v31, v31, v32
	v_add_f32_e32 v30, v30, v31
	v_and_b32_e32 v31, 64, v223
	v_add_u32_e32 v31, 64, v31
	v_xor_b32_e32 v32, 1, v223
	v_cmp_lt_i32_e64 s[46:47], v32, v31
	s_nop 1
	v_cndmask_b32_e64 v32, v223, v32, s[46:47]
	v_lshlrev_b32_e32 v55, 2, v32
	s_nop 1
	v_add_f32_dpp v30, v30, v30 quad_perm:[1,0,3,2] row_mask:0xf bank_mask:0xf
	v_xor_b32_e32 v32, 2, v223
	v_cmp_lt_i32_e64 s[46:47], v32, v31
	s_nop 1
	v_cndmask_b32_e64 v32, v223, v32, s[46:47]
	v_lshlrev_b32_e32 v57, 2, v32
	s_nop 1
	v_add_f32_dpp v30, v30, v30 quad_perm:[2,3,0,1] row_mask:0xf bank_mask:0xf
	v_xor_b32_e32 v32, 4, v223
	v_cmp_lt_i32_e64 s[46:47], v32, v31
	s_nop 1
	v_cndmask_b32_e64 v32, v223, v32, s[46:47]
	v_lshlrev_b32_e32 v59, 2, v32
	s_nop 1
	v_add_f32_dpp v30, v30, v30 row_half_mirror row_mask:0xf bank_mask:0xf
	v_xor_b32_e32 v32, 8, v223
	v_cmp_lt_i32_e64 s[46:47], v32, v31
	s_nop 1
	v_cndmask_b32_e64 v31, v223, v32, s[46:47]
	v_lshlrev_b32_e32 v81, 2, v31
	s_nop 1
	v_add_f32_dpp v30, v30, v30 row_mirror row_mask:0xf bank_mask:0xf
	v_fmamk_f32 v30, v30, 0x3c000000, v216
	v_cmp_gt_f32_e64 s[46:47], s26, v30
	v_mul_f32_e32 v31, 0x4b800000, v30
	s_nop 0
	v_cndmask_b32_e64 v30, v30, v31, s[46:47]
	v_rsq_f32_e32 v30, v30
	s_nop 0
	v_mul_f32_e32 v31, 0x45800000, v30
	v_cndmask_b32_e64 v30, v30, v31, s[46:47]
	v_mul_f32_e32 v85, 0x3dd53b94, v30
	v_mov_b64_e32 v[30:31], v[98:99]
	v_mov_b64_e32 v[32:33], v[100:101]
	v_mov_b64_e32 v[88:89], v[94:95]
	v_mov_b64_e32 v[90:91], v[96:97]
	v_mul_f32_e32 v86, v85, v86
	v_mul_f32_e32 v69, v85, v69
	v_mul_f32_e32 v68, v85, v68
	v_mul_f32_e32 v84, v85, v84
	v_mul_f32_e32 v71, v85, v71
	v_mul_f32_e32 v70, v85, v70
	v_mul_f32_e32 v30, v30, v69
	v_mul_f32_e32 v86, v88, v86
	v_mul_f32_e32 v31, v31, v68
	v_mul_f32_e32 v84, v89, v84
	v_cvt_pk_bf16_f32 v86, v86, v84
	v_mul_f32_e32 v71, v90, v71
	v_mul_f32_e32 v70, v91, v70
	v_cvt_pk_bf16_f32 v87, v71, v70
	v_cvt_pk_bf16_f32 v88, v30, v31
	v_mul_f32_e32 v30, v85, v67
	v_mul_f32_e32 v31, v85, v66
	v_mul_f32_e32 v30, v32, v30
	v_mul_f32_e32 v31, v33, v31
	v_cvt_pk_bf16_f32 v89, v30, v31
	global_store_dwordx4 v[64:65], v[86:89], off
	s_nop 1
	v_mov_b64_e32 v[30:31], v[106:107]
	v_mov_b64_e32 v[32:33], v[108:109]
	s_nop 0
	v_mov_b64_e32 v[64:65], v[102:103]
	v_mov_b64_e32 v[66:67], v[104:105]
	v_lshlrev_b32_e32 v68, 16, v26
	v_and_b32_e32 v69, 0xffff0000, v26
	v_pk_mul_f32 v[70:71], v[68:69], v[68:69]
	v_lshlrev_b32_e32 v84, 16, v27
	v_and_b32_e32 v85, 0xffff0000, v27
	v_pk_mul_f32 v[26:27], v[84:85], v[84:85]
	v_add_f32_e32 v70, v70, v71
	v_lshlrev_b32_e32 v86, 16, v28
	v_and_b32_e32 v87, 0xffff0000, v28
	v_add_f32_e32 v26, v26, v70
	v_pk_mul_f32 v[88:89], v[86:87], v[86:87]
	v_add_f32_e32 v26, v27, v26
	v_lshlrev_b32_e32 v90, 16, v29
	v_and_b32_e32 v91, 0xffff0000, v29
	v_add_f32_e32 v26, v88, v26
	v_pk_mul_f32 v[28:29], v[90:91], v[90:91]
	v_add_f32_e32 v26, v89, v26
	v_add_f32_e32 v26, v28, v26
	v_add_f32_e32 v26, v29, v26
	s_nop 1
	v_add_f32_dpp v26, v26, v26 quad_perm:[1,0,3,2] row_mask:0xf bank_mask:0xf
	s_nop 1
	v_add_f32_dpp v26, v26, v26 quad_perm:[2,3,0,1] row_mask:0xf bank_mask:0xf
	s_nop 1
	v_add_f32_dpp v26, v26, v26 row_half_mirror row_mask:0xf bank_mask:0xf
	v_fmamk_f32 v26, v26, 0x3c800000, v216
	v_cmp_gt_f32_e64 s[46:47], s26, v26
	v_mul_f32_e32 v27, 0x4b800000, v26
	s_nop 0
	v_cndmask_b32_e64 v26, v26, v27, s[46:47]
	v_rsq_f32_e32 v26, v26
	s_nop 0
	v_mul_f32_e32 v27, 0x45800000, v26
	v_cndmask_b32_e64 v26, v26, v27, s[46:47]
	v_mul_f32_e32 v70, 0x3dd53b94, v26
	v_pk_mul_f32 v[26:27], v[70:71], v[68:69] op_sel_hi:[0,1]
	v_pk_mul_f32 v[28:29], v[70:71], v[84:85] op_sel_hi:[0,1]
	v_pk_mul_f32 v[26:27], v[64:65], v[26:27]
	v_pk_mul_f32 v[64:65], v[70:71], v[86:87] op_sel_hi:[0,1]
	v_pk_mul_f32 v[30:31], v[30:31], v[64:65]
	v_pk_mul_f32 v[64:65], v[70:71], v[90:91] op_sel_hi:[0,1]
	v_pk_mul_f32 v[28:29], v[66:67], v[28:29]
	v_pk_mul_f32 v[32:33], v[32:33], v[64:65]
	s_and_saveexec_b64 s[20:21], vcc
	s_cbranch_execz .LBB0_172
; __device__ __forceinline__ void e2_row(CArgs& a, int l, int r, int lane, int dup, const E2Regs& g) {
;     ...
;       if (lat) { const float pos = (float)(li8 < 4 ? prow : pcol); const bool second = ((li8 >> 1) & 1) != 0;
; #pragma unroll
;           for (int e = 0; e < 8; ++e) { const float ang = pos * __builtin_amdgcn_exp2f(-(float)(8 * (li8 & 1) + e) * (13.287712379549449f / 16.f));
;               const float c = __cosf(ang), sn = __sinf(ang), p = __shfl_xor(y[e], 2); y[e] = second ? (p * sn + y[e] * c) : (y[e] * c - p * sn); } }
	v_add_u32_e32 v64, 0xffffff00, v83
	v_lshrrev_b32_e32 v64, 6, v64
	v_and_b32_e32 v65, 63, v83
	v_cndmask_b32_e64 v64, v65, v64, s[38:39]
	v_cvt_f32_u32_e32 v83, v64
	ds_bpermute_b32 v68, v57, v26
	ds_bpermute_b32 v69, v57, v27
	ds_bpermute_b32 v84, v57, v28
	v_mul_f32_e32 v64, v72, v83
	v_mul_f32_e32 v65, 0.15915494, v64
	v_cos_f32_e32 v64, v65
	v_sin_f32_e32 v66, v65
	v_mul_f32_e32 v65, v73, v83
	v_mul_f32_e32 v67, 0.15915494, v65
	v_cos_f32_e32 v65, v67
	v_sin_f32_e32 v67, v67
	ds_bpermute_b32 v85, v57, v29
	ds_bpermute_b32 v88, v57, v30
	ds_bpermute_b32 v89, v57, v31
	s_waitcnt lgkmcnt(4)
	v_pk_mul_f32 v[66:67], v[66:67], v[68:69]
	v_mul_f32_e32 v68, v74, v83
	v_mul_f32_e32 v69, 0.15915494, v68
	v_cos_f32_e32 v68, v69
	v_sin_f32_e32 v70, v69
	v_mul_f32_e32 v69, v75, v83
	v_mul_f32_e32 v71, 0.15915494, v69
	v_cos_f32_e32 v69, v71
	v_sin_f32_e32 v71, v71
	ds_bpermute_b32 v92, v57, v32
	ds_bpermute_b32 v93, v57, v33
	v_cndmask_b32_e64 v67, v67, -v67, s[40:41]
	s_waitcnt lgkmcnt(4)
	v_pk_mul_f32 v[70:71], v[70:71], v[84:85]
	v_mul_f32_e32 v84, v76, v83
	v_mul_f32_e32 v85, 0.15915494, v84
	v_cos_f32_e32 v84, v85
	v_sin_f32_e32 v86, v85
	v_mul_f32_e32 v85, v77, v83
	v_mul_f32_e32 v87, 0.15915494, v85
	v_cos_f32_e32 v85, v87
	v_sin_f32_e32 v87, v87
	v_cndmask_b32_e64 v66, v66, -v66, s[40:41]
	v_cndmask_b32_e64 v71, v71, -v71, s[40:41]
	v_cndmask_b32_e64 v70, v70, -v70, s[40:41]
	s_waitcnt lgkmcnt(2)
	v_pk_mul_f32 v[86:87], v[86:87], v[88:89]
	v_mul_f32_e32 v88, v78, v83
	v_mul_f32_e32 v83, v79, v83
	v_mul_f32_e32 v89, 0.15915494, v88
	v_mul_f32_e32 v83, 0.15915494, v83
	v_sin_f32_e32 v90, v89
	v_sin_f32_e32 v91, v83
	v_cos_f32_e32 v88, v89
	v_cos_f32_e32 v89, v83
	v_cndmask_b32_e64 v87, v87, -v87, s[40:41]
	s_waitcnt lgkmcnt(0)
	v_pk_mul_f32 v[90:91], v[90:91], v[92:93]
	v_cndmask_b32_e64 v86, v86, -v86, s[40:41]
	v_cndmask_b32_e64 v91, v91, -v91, s[40:41]
	v_cndmask_b32_e64 v90, v90, -v90, s[40:41]
	v_pk_fma_f32 v[32:33], v[88:89], v[32:33], v[90:91]
	v_pk_fma_f32 v[30:31], v[84:85], v[30:31], v[86:87]
	v_pk_fma_f32 v[28:29], v[68:69], v[28:29], v[70:71]
	v_pk_fma_f32 v[26:27], v[64:65], v[26:27], v[66:67]

; __device__ __forceinline__ unsigned cvt_pk_bf16(float lo, float hi) { unsigned r; asm volatile("v_cvt_pk_bf16_f32 %0, %1, %2" : "=v"(r) : "v"(lo), "v"(hi)); return r; }
; #define E2_UNPK(wv_, arr_) float arr_[8] = {bflo(wv_[0]), bfhi(wv_[0]), bflo(wv_[1]), bfhi(wv_[1]), bflo(wv_[2]), bfhi(wv_[2]), bflo(wv_[3]), bfhi(wv_[3])}
; __device__ __forceinline__ void e2_row(CArgs& a, int l, int r, int lane, int dup, const E2Regs& g) {
;     ...
;     { E2_UNPK(g.kn, x); float ss = 0.f;
; #pragma unroll
;       for (int e = 0; e < 8; ++e) ss += x[e] * x[e];
; #pragma unroll
;       for (int m = 1; m < 16; m <<= 1) ss += __shfl_xor(ss, m);
;       const float rs = rsqrtf(ss * (1.f / 128.f) + EPS);
;       const float* gg = a.in[I_BKNN] + l * 128 + 8 * li; const f32x4 ga = *(const f32x4*)gg, gb = *(const f32x4*)(gg + 4);
;       u32x4 o; o.x = cvt_pk_bf16(x[0] * rs * ga.x, x[1] * rs * ga.y); o.y = cvt_pk_bf16(x[2] * rs * ga.z, x[3] * rs * ga.w);
;       o.z = cvt_pk_bf16(x[4] * rs * gb.x, x[5] * rs * gb.y); o.w = cvt_pk_bf16(x[6] * rs * gb.z, x[7] * rs * gb.w);
;       *(u32x4*)(KB + h16 * 192 + 8 * li) = o; }
.LBB0_174:
	s_or_b64 exec, exec, s[14:15]
	v_and_b32_e32 v63, 0xffff0000, v18
	v_lshlrev_b32_e32 v62, 16, v18
	v_mul_f32_e32 v22, v63, v63
	v_and_b32_e32 v28, 0xffff0000, v19
	v_lshlrev_b32_e32 v29, 16, v19
	v_fmac_f32_e32 v22, v62, v62
	v_pk_mul_f32 v[18:19], v[28:29], v[28:29]
	v_and_b32_e32 v30, 0xffff0000, v20
	v_add_f32_e32 v19, v19, v22
	v_lshlrev_b32_e32 v31, 16, v20
	v_add_f32_e32 v22, v18, v19
	v_pk_mul_f32 v[18:19], v[30:31], v[30:31]
	v_and_b32_e32 v32, 0xffff0000, v21
	v_add_f32_e32 v19, v19, v22
	v_lshlrev_b32_e32 v33, 16, v21
	v_add_f32_e32 v20, v18, v19
	v_pk_mul_f32 v[18:19], v[32:33], v[32:33]
	s_nop 0
	v_add_f32_e32 v19, v19, v20
	v_mov_b64_e32 v[20:21], v[114:115]
	v_mov_b64_e32 v[22:23], v[116:117]
	v_mov_b64_e32 v[24:25], v[110:111]
	v_mov_b64_e32 v[26:27], v[112:113]
	v_add_f32_e32 v18, v18, v19
	s_nop 1
	v_add_f32_dpp v18, v18, v18 quad_perm:[1,0,3,2] row_mask:0xf bank_mask:0xf
	s_nop 1
	v_add_f32_dpp v18, v18, v18 quad_perm:[2,3,0,1] row_mask:0xf bank_mask:0xf
	s_nop 1
	v_add_f32_dpp v18, v18, v18 row_half_mirror row_mask:0xf bank_mask:0xf
	s_nop 1
	v_add_f32_dpp v18, v18, v18 row_mirror row_mask:0xf bank_mask:0xf
	v_fmamk_f32 v18, v18, 0x3c000000, v216
	v_cmp_gt_f32_e32 vcc, s26, v18
	v_mul_f32_e32 v19, 0x4b800000, v18
	s_nop 0
	v_cndmask_b32_e32 v18, v18, v19, vcc
	v_rsq_f32_e32 v18, v18
	s_nop 0
	v_mul_f32_e32 v19, 0x45800000, v18
	v_cndmask_b32_e32 v64, v18, v19, vcc
	v_mul_f32_e32 v18, v64, v62
	v_mul_f32_e32 v19, v64, v63
	v_mul_f32_e32 v18, v24, v18
	v_mul_f32_e32 v19, v25, v19
	v_cvt_pk_bf16_f32 v18, v18, v19
	v_mul_f32_e32 v19, v64, v29
	v_mul_f32_e32 v24, v64, v28
	v_mul_f32_e32 v19, v26, v19
	v_mul_f32_e32 v24, v27, v24
	v_cvt_pk_bf16_f32 v19, v19, v24
	v_mul_f32_e32 v24, v64, v31
	v_mul_f32_e32 v20, v20, v24
	v_mul_f32_e32 v24, v64, v30
	v_mul_f32_e32 v21, v21, v24
	v_cvt_pk_bf16_f32 v20, v20, v21
	v_mul_f32_e32 v21, v64, v33
	v_mul_f32_e32 v21, v22, v21
	v_mul_f32_e32 v22, v64, v32
	v_mul_f32_e32 v22, v23, v22
	v_cvt_pk_bf16_f32 v21, v21, v22
	v_add_co_u32_e32 v22, vcc, 0x24900000, v60
	s_nop 1
	v_addc_co_u32_e32 v23, vcc, 0, v61, vcc
	global_store_dwordx4 v[22:23], v[18:21], off
	s_nop 1
	s_and_saveexec_b64 s[20:21], s[44:45]
	s_cbranch_execz .LBB0_169
; __device__ __forceinline__ unsigned cvt_pk_bf16(float lo, float hi) { unsigned r; asm volatile("v_cvt_pk_bf16_f32 %0, %1, %2" : "=v"(r) : "v"(lo), "v"(hi)); return r; }
; #define E2_UNPK(wv_, arr_) float arr_[8] = {bflo(wv_[0]), bfhi(wv_[0]), bflo(wv_[1]), bfhi(wv_[1]), bflo(wv_[2]), bfhi(wv_[2]), bflo(wv_[3]), bfhi(wv_[3])}
; __device__ __forceinline__ void e2_row(CArgs& a, int l, int r, int lane, int dup, const E2Regs& g) {
;     ...
;     { E2_UNPK(g.qn, x); float ss = 0.f;
; #pragma unroll
;       for (int e = 0; e < 8; ++e) ss += x[e] * x[e];
; #pragma unroll
;       for (int m = 1; m < 16; m <<= 1) ss += __shfl_xor(ss, m);
;       const float rs = rsqrtf(ss * (1.f / 128.f) + EPS) * QSCALE_B;
;       const float* gg = a.in[I_BQNN] + l * 128 + 8 * li; const f32x4 ga = *(const f32x4*)gg, gb = *(const f32x4*)(gg + 4);
;       u32x4 o; o.x = cvt_pk_bf16(x[0] * rs * ga.x, x[1] * rs * ga.y); o.y = cvt_pk_bf16(x[2] * rs * ga.z, x[3] * rs * ga.w);
;       o.z = cvt_pk_bf16(x[4] * rs * gb.x, x[5] * rs * gb.y); o.w = cvt_pk_bf16(x[6] * rs * gb.z, x[7] * rs * gb.w);
;       *(u32x4*)(Q + h16 * 192 + 8 * li) = o; }
;     { E2_UNPK(g.qr, x); float ss = 0.f;
; #pragma unroll
;       for (int e = 0; e < 8; ++e) ss += x[e] * x[e];
; #pragma unroll
;       for (int m = 1; m < 8; m <<= 1) ss += __shfl_xor(ss, m);
;       const float rs = rsqrtf(ss * (1.f / 64.f) + EPS) * QSCALE_B;
;       const float* gg = a.in[I_BQRN] + l * 64 + 8 * li8; const f32x4 ga = *(const f32x4*)gg, gb = *(const f32x4*)(gg + 4);
;       float y[8] = {x[0] * rs * ga.x, x[1] * rs * ga.y, x[2] * rs * ga.z, x[3] * rs * ga.w, x[4] * rs * gb.x, x[5] * rs * gb.y, x[6] * rs * gb.z, x[7] * rs * gb.w};
;       if (lat) { const float pos = (float)(li8 < 4 ? prow : pcol); const bool second = ((li8 >> 1) & 1) != 0;
; #pragma unroll
;           for (int e = 0; e < 8; ++e) { const float ang = pos * __builtin_amdgcn_exp2f(-(float)(8 * (li8 & 1) + e) * (13.287712379549449f / 16.f));
;               const float c = __cosf(ang), sn = __sinf(ang), p = __shfl_xor(y[e], 2); y[e] = second ? (p * sn + y[e] * c) : (y[e] * c - p * sn); } }
;       u32x4 o; o.x = cvt_pk_bf16(y[0], y[1]); o.y = cvt_pk_bf16(y[2], y[3]); o.z = cvt_pk_bf16(y[4], y[5]); o.w = cvt_pk_bf16(y[6], y[7]);
;       if (lane < 32) { *(u32x4*)(Q + h8 * 192 + 128 + 8 * li8) = o; *(u32x4*)(KB + h8 * 192 + 128 + 8 * li8) = g.kr; } }
	v_mov_b64_e32 v[18:19], v[94:95]
	v_mov_b64_e32 v[20:21], v[96:97]
	v_mov_b64_e32 v[22:23], v[98:99]
	v_mov_b64_e32 v[24:25], v[100:101]
	v_and_b32_e32 v61, 0xffff0000, v14
	v_lshlrev_b32_e32 v60, 16, v14
	v_and_b32_e32 v26, 0xffff0000, v15
	v_lshlrev_b32_e32 v27, 16, v15
	v_mul_f32_e32 v62, v61, v61
	v_pk_mul_f32 v[14:15], v[26:27], v[26:27]
	v_fmac_f32_e32 v62, v60, v60
	v_and_b32_e32 v28, 0xffff0000, v16
	v_lshlrev_b32_e32 v29, 16, v16
	v_add_f32_e32 v15, v15, v62
	v_pk_mul_f32 v[30:31], v[28:29], v[28:29]
	v_add_f32_e32 v14, v14, v15
	v_and_b32_e32 v16, 0xffff0000, v17
	v_lshlrev_b32_e32 v17, 16, v17
	v_add_f32_e32 v14, v31, v14
	v_pk_mul_f32 v[32:33], v[16:17], v[16:17]
	v_add_f32_e32 v14, v30, v14
	v_add_f32_e32 v14, v33, v14
	v_add_f32_e32 v14, v32, v14
	s_nop 1
	s_mov_b32 s4, 0x20d00000
	v_add_f32_dpp v14, v14, v14 quad_perm:[1,0,3,2] row_mask:0xf bank_mask:0xf
	s_nop 1
	v_add_f32_dpp v14, v14, v14 quad_perm:[2,3,0,1] row_mask:0xf bank_mask:0xf
	s_nop 1
	v_add_f32_dpp v30, v14, v14 row_half_mirror row_mask:0xf bank_mask:0xf
	s_nop 1
	v_lshl_add_u64 v[14:15], s[56:57], 0, v[52:53]
	v_add_f32_dpp v30, v30, v30 row_mirror row_mask:0xf bank_mask:0xf
	v_fmamk_f32 v30, v30, 0x3c000000, v216
	v_mul_f32_e32 v31, 0x4b800000, v30
	v_cmp_gt_f32_e32 vcc, s26, v30
	s_nop 1
	v_cndmask_b32_e32 v30, v30, v31, vcc
	v_rsq_f32_e32 v32, v30
	v_add_co_u32_e64 v30, s[44:45], s4, v14
	v_mul_f32_e32 v33, 0x45800000, v32
	v_cndmask_b32_e32 v32, v32, v33, vcc
	v_mul_f32_e32 v32, 0x3dd53b94, v32
	v_mul_f32_e32 v33, v32, v60
	v_mul_f32_e32 v60, v32, v61
	v_addc_co_u32_e64 v31, s[44:45], 0, v15, s[44:45]
	v_mul_f32_e32 v27, v32, v27
	v_mul_f32_e32 v26, v32, v26
	v_mul_f32_e32 v29, v32, v29
	v_mul_f32_e32 v28, v32, v28
	v_mul_f32_e32 v17, v32, v17
	v_mul_f32_e32 v16, v32, v16
	v_mul_f32_e32 v18, v18, v33
	v_mul_f32_e32 v19, v19, v60
	v_mul_f32_e32 v20, v20, v27
	v_mul_f32_e32 v21, v21, v26
	v_mul_f32_e32 v22, v22, v29
	v_mul_f32_e32 v23, v23, v28
	v_mul_f32_e32 v24, v24, v17
	v_mul_f32_e32 v25, v25, v16
	v_cvt_pk_bf16_f32 v16, v18, v19
	v_cvt_pk_bf16_f32 v17, v20, v21
	v_cvt_pk_bf16_f32 v18, v22, v23
	v_cvt_pk_bf16_f32 v19, v24, v25
	global_store_dwordx4 v[30:31], v[16:19], off
	s_nop 1
	v_mov_b64_e32 v[16:17], v[102:103]
	v_mov_b64_e32 v[18:19], v[104:105]
	s_nop 0
	v_mov_b64_e32 v[22:23], v[106:107]
	v_mov_b64_e32 v[24:25], v[108:109]
	v_lshlrev_b32_e32 v26, 16, v10
	v_and_b32_e32 v27, 0xffff0000, v10
	v_lshlrev_b32_e32 v10, 16, v11
	v_and_b32_e32 v11, 0xffff0000, v11
	v_pk_mul_f32 v[20:21], v[26:27], v[26:27]
	v_pk_mul_f32 v[30:31], v[10:11], v[10:11]
	v_add_f32_e32 v20, v20, v21
	v_lshlrev_b32_e32 v28, 16, v12
	v_and_b32_e32 v29, 0xffff0000, v12
	v_add_f32_e32 v20, v30, v20
	v_pk_mul_f32 v[32:33], v[28:29], v[28:29]
	v_add_f32_e32 v20, v31, v20
	v_lshlrev_b32_e32 v12, 16, v13
	v_and_b32_e32 v13, 0xffff0000, v13
	v_add_f32_e32 v20, v32, v20
	v_pk_mul_f32 v[60:61], v[12:13], v[12:13]
	v_add_f32_e32 v20, v33, v20
	v_add_f32_e32 v20, v60, v20
	v_add_f32_e32 v20, v61, v20
	ds_bpermute_b32 v21, v55, v20
	v_mul_hi_i32 v30, v82, s94
	v_lshrrev_b32_e32 v31, 31, v30
	v_ashrrev_i32_e32 v30, 11, v30
	v_add_u32_e32 v30, v30, v31
	s_waitcnt lgkmcnt(0)
	v_add_f32_e32 v20, v20, v21
	s_nop 1
	v_add_f32_dpp v20, v20, v20 quad_perm:[2,3,0,1] row_mask:0xf bank_mask:0xf
	s_nop 1
	v_add_f32_dpp v20, v20, v20 row_half_mirror row_mask:0xf bank_mask:0xf
	v_fmamk_f32 v20, v20, 0x3c800000, v216
	v_mul_f32_e32 v21, 0x4b800000, v20
	v_cmp_gt_f32_e32 vcc, s26, v20
	s_nop 1
	v_cndmask_b32_e32 v20, v20, v21, vcc
	v_rsq_f32_e32 v21, v20
	v_mul_i32_i24_e32 v20, 0x1100, v30
	v_sub_u32_e32 v20, v82, v20
	v_cmp_lt_i32_e64 s[44:45], s78, v20
	v_mul_f32_e32 v30, 0x45800000, v21
	v_cndmask_b32_e32 v21, v21, v30, vcc
	v_mul_f32_e32 v30, 0x3dd53b94, v21
	v_pk_mul_f32 v[26:27], v[30:31], v[26:27] op_sel_hi:[0,1]
	v_pk_mul_f32 v[32:33], v[30:31], v[10:11] op_sel_hi:[0,1]
	v_pk_mul_f32 v[28:29], v[30:31], v[28:29] op_sel_hi:[0,1]
	v_pk_mul_f32 v[30:31], v[30:31], v[12:13] op_sel_hi:[0,1]
	v_pk_mul_f32 v[10:11], v[16:17], v[26:27]
	v_pk_mul_f32 v[12:13], v[18:19], v[32:33]
	v_pk_mul_f32 v[16:17], v[22:23], v[28:29]
	v_pk_mul_f32 v[18:19], v[24:25], v[30:31]
	s_and_saveexec_b64 s[22:23], s[44:45]
	s_cbranch_execz .LBB0_177
	v_add_u32_e32 v21, 0xffffff00, v20
	v_lshrrev_b32_e32 v21, 6, v21
	v_and_b32_e32 v20, 63, v20
	v_cndmask_b32_e64 v20, v20, v21, s[38:39]
	v_cvt_f32_u32_e32 v61, v20
	ds_bpermute_b32 v24, v57, v10
	ds_bpermute_b32 v25, v57, v11
	ds_bpermute_b32 v28, v57, v12
	v_mul_f32_e32 v20, v72, v61
	v_mul_f32_e32 v21, 0.15915494, v20
	v_cos_f32_e32 v20, v21
	v_sin_f32_e32 v22, v21
	v_mul_f32_e32 v21, v73, v61
	v_mul_f32_e32 v23, 0.15915494, v21
	v_cos_f32_e32 v21, v23
	v_sin_f32_e32 v23, v23
	ds_bpermute_b32 v29, v57, v13
	ds_bpermute_b32 v32, v57, v16
	ds_bpermute_b32 v33, v57, v17
	s_waitcnt lgkmcnt(4)
	v_pk_mul_f32 v[22:23], v[22:23], v[24:25]
	v_mul_f32_e32 v24, v74, v61
	v_mul_f32_e32 v25, 0.15915494, v24
	v_cos_f32_e32 v24, v25
	v_sin_f32_e32 v26, v25
	v_mul_f32_e32 v25, v75, v61
	v_mul_f32_e32 v27, 0.15915494, v25
	v_cos_f32_e32 v25, v27
	v_sin_f32_e32 v27, v27
	ds_bpermute_b32 v62, v57, v18
	ds_bpermute_b32 v63, v57, v19
	v_cndmask_b32_e64 v23, v23, -v23, s[40:41]
	s_waitcnt lgkmcnt(4)
	v_pk_mul_f32 v[26:27], v[26:27], v[28:29]
	v_mul_f32_e32 v28, v76, v61
	v_mul_f32_e32 v29, 0.15915494, v28
	v_cos_f32_e32 v28, v29
	v_sin_f32_e32 v30, v29
	v_mul_f32_e32 v29, v77, v61
	v_mul_f32_e32 v31, 0.15915494, v29
	v_cos_f32_e32 v29, v31
	v_sin_f32_e32 v31, v31
	v_cndmask_b32_e64 v22, v22, -v22, s[40:41]
	v_cndmask_b32_e64 v27, v27, -v27, s[40:41]
	v_cndmask_b32_e64 v26, v26, -v26, s[40:41]
	s_waitcnt lgkmcnt(2)
	v_pk_mul_f32 v[30:31], v[30:31], v[32:33]
	v_mul_f32_e32 v32, v78, v61
	v_mul_f32_e32 v33, 0.15915494, v32
	v_cos_f32_e32 v32, v33
	v_sin_f32_e32 v60, v33
	v_mul_f32_e32 v33, v79, v61
	v_mul_f32_e32 v61, 0.15915494, v33
	v_cos_f32_e32 v33, v61
	v_sin_f32_e32 v61, v61
	v_cndmask_b32_e64 v31, v31, -v31, s[40:41]
	v_cndmask_b32_e64 v30, v30, -v30, s[40:41]
	v_pk_fma_f32 v[16:17], v[28:29], v[16:17], v[30:31]
	s_waitcnt lgkmcnt(0)
	v_pk_mul_f32 v[60:61], v[60:61], v[62:63]
	v_pk_fma_f32 v[12:13], v[24:25], v[12:13], v[26:27]
	v_cndmask_b32_e64 v61, v61, -v61, s[40:41]
	v_cndmask_b32_e64 v60, v60, -v60, s[40:41]
	v_pk_fma_f32 v[18:19], v[32:33], v[18:19], v[60:61]
	v_pk_fma_f32 v[10:11], v[20:21], v[10:11], v[22:23]

; __device__ __forceinline__ unsigned cvt_pk_bf16(float lo, float hi) { unsigned r; asm volatile("v_cvt_pk_bf16_f32 %0, %1, %2" : "=v"(r) : "v"(lo), "v"(hi)); return r; }
; __device__ __forceinline__ float wave_sum(float v) {
; #pragma unroll
;     for (int o = 1; o < 64; o <<= 1) v += __shfl_xor(v, o);
;     return v;
; __device__ __forceinline__ void phase_norm(CArgs& a, int l, int which) {
;     ...
;         for (int u = 0; u < 2; ++u) { float ss = 0.f;
; #pragma unroll
;             for (int j = 0; j < 8; ++j) ss += (x[u][j].x * x[u][j].x + x[u][j].y * x[u][j].y) + (x[u][j].z * x[u][j].z + x[u][j].w * x[u][j].w);
;             const float rs = rsqrtf(wave_sum(ss) * (1.f / DM) + EPS);
;             if (!ok[u]) continue;
;             bf16_t* o = H + (size_t)(r0 + u * NGW) * DM;
; #pragma unroll
;             for (int j = 0; j < 8; ++j) { const int c = 4 * lane + 256 * j; const f32x4 g = *(const f32x4*)(gn + c), s1 = *(const f32x4*)(sc[u] + c), s0 = *(const f32x4*)(sh[u] + c);
;                 const f32x4 y = (x[u][j] * rs) * g * (1.f + s1) + s0;
;                 u32x2 w; w.x = cvt_pk_bf16(y.x, y.y); w.y = cvt_pk_bf16(y.z, y.w); *(u32x2*)(o + c) = w; } }
.LBB0_337:
	s_or_b64 exec, exec, s[20:21]
	v_cndmask_b32_e64 v99, v110, 4, s[40:41]
	s_waitcnt vmcnt(0)
	v_mul_f32_e32 v110, v63, v63
	v_mul_f32_e32 v111, v65, v65
	v_fmac_f32_e32 v110, v62, v62
	v_fmac_f32_e32 v111, v64, v64
	v_add_f32_e32 v110, v110, v111
	v_mul_f32_e32 v111, v59, v59
	v_mul_f32_e32 v113, v61, v61
	v_fmac_f32_e32 v111, v58, v58
	v_fmac_f32_e32 v113, v60, v60
	v_add_f32_e32 v111, v111, v113
	v_add_f32_e32 v110, v111, v110
	v_mul_f32_e32 v111, v51, v51
	v_mul_f32_e32 v113, v53, v53
	v_fmac_f32_e32 v111, v50, v50
	v_fmac_f32_e32 v113, v52, v52
	v_add_f32_e32 v111, v111, v113
	v_add_f32_e32 v110, v111, v110
	v_mul_f32_e32 v111, v43, v43
	v_mul_f32_e32 v113, v45, v45
	v_fmac_f32_e32 v111, v42, v42
	v_fmac_f32_e32 v113, v44, v44
	v_add_f32_e32 v111, v111, v113
	v_add_f32_e32 v110, v111, v110
	v_mul_f32_e32 v111, v35, v35
	v_mul_f32_e32 v113, v37, v37
	v_fmac_f32_e32 v111, v34, v34
	v_fmac_f32_e32 v113, v36, v36
	v_add_f32_e32 v111, v111, v113
	v_add_f32_e32 v110, v111, v110
	v_mul_f32_e32 v111, v27, v27
	v_mul_f32_e32 v113, v29, v29
	v_fmac_f32_e32 v111, v26, v26
	v_fmac_f32_e32 v113, v28, v28
	v_add_f32_e32 v111, v111, v113
	v_add_f32_e32 v110, v111, v110
	v_mul_f32_e32 v111, v19, v19
	v_mul_f32_e32 v113, v21, v21
	v_fmac_f32_e32 v111, v18, v18
	v_fmac_f32_e32 v113, v20, v20
	v_add_f32_e32 v111, v111, v113
	v_add_f32_e32 v110, v111, v110
	v_mul_f32_e32 v111, v11, v11
	v_mul_f32_e32 v113, v13, v13
	v_fmac_f32_e32 v111, v10, v10
	v_fmac_f32_e32 v113, v12, v12
	v_add_f32_e32 v111, v111, v113
	v_add_f32_e32 v110, v111, v110
	ds_bpermute_b32 v111, v69, v110
	s_and_b64 s[4:5], s[46:47], s[42:43]
	s_xor_b64 s[4:5], s[4:5], -1
	v_lshlrev_b32_e32 v124, 2, v84
	v_lshlrev_b32_e32 v122, 2, v86
	s_waitcnt lgkmcnt(0)
	v_add_f32_e32 v110, v110, v111
	ds_bpermute_b32 v111, v85, v110
	v_lshlrev_b32_e32 v120, 2, v88
	v_lshlrev_b32_e32 v118, 2, v90
	v_lshlrev_b32_e32 v116, 2, v94
	v_lshlrev_b32_e32 v114, 2, v98
	s_waitcnt lgkmcnt(0)
	v_add_f32_e32 v110, v110, v111
	s_nop 1
	v_add_f32_dpp v110, v110, v110 row_half_mirror row_mask:0xf bank_mask:0xf
	s_nop 1
	v_add_f32_dpp v110, v110, v110 row_mirror row_mask:0xf bank_mask:0xf
	ds_bpermute_b32 v111, v91, v110
	s_waitcnt lgkmcnt(0)
	v_add_f32_e32 v111, v110, v111
	ds_bpermute_b32 v113, v95, v111
	v_lshlrev_b32_e32 v110, 2, v102
	s_and_saveexec_b64 s[20:21], s[4:5]
	s_cbranch_execz .LBB0_339
	v_mul_hi_i32_i24_e32 v127, 0xc000, v103
	v_mul_i32_i24_e32 v126, 0xc000, v103
	v_lshl_add_u64 v[126:127], s[72:73], 0, v[126:127]
	v_lshl_add_u64 v[128:129], v[126:127], 0, s[96:97]
	v_lshl_add_u64 v[132:133], v[128:129], 0, v[0:1]
	global_load_dwordx4 v[134:137], v[82:83], off
	global_load_dwordx4 v[138:141], v[132:133], off
	v_lshl_add_u64 v[132:133], v[126:127], 0, v[0:1]
	global_load_dwordx4 v[142:145], v[132:133], off
	s_waitcnt lgkmcnt(0)
	v_add_f32_e32 v103, v111, v113
	v_fmamk_f32 v103, v103, 0x3a000000, v216
	v_cmp_gt_f32_e32 vcc, s26, v103
	v_mul_f32_e32 v111, 0x4b800000, v103
	v_lshlrev_b64 v[146:147], 12, v[66:67]
	v_cndmask_b32_e32 v103, v103, v111, vcc
	v_rsq_f32_e32 v103, v103
	v_mov_b32_e32 v125, v1
	v_mov_b32_e32 v123, v1
	v_mov_b32_e32 v121, v1
	v_mul_f32_e32 v111, 0x45800000, v103
	v_cndmask_b32_e32 v130, v103, v111, vcc
	v_pk_mul_f32 v[64:65], v[64:65], v[130:131] op_sel_hi:[1,0]
	v_pk_mul_f32 v[62:63], v[62:63], v[130:131] op_sel_hi:[1,0]
	v_pk_mul_f32 v[58:59], v[58:59], v[130:131] op_sel_hi:[1,0]
	v_pk_mul_f32 v[60:61], v[60:61], v[130:131] op_sel_hi:[1,0]
	v_pk_mul_f32 v[52:53], v[52:53], v[130:131] op_sel_hi:[1,0]
	v_pk_mul_f32 v[50:51], v[50:51], v[130:131] op_sel_hi:[1,0]
	v_pk_mul_f32 v[44:45], v[44:45], v[130:131] op_sel_hi:[1,0]
	v_pk_mul_f32 v[42:43], v[42:43], v[130:131] op_sel_hi:[1,0]
	v_mov_b32_e32 v119, v1
	v_pk_mul_f32 v[36:37], v[36:37], v[130:131] op_sel_hi:[1,0]
	v_pk_mul_f32 v[34:35], v[34:35], v[130:131] op_sel_hi:[1,0]
	v_mov_b32_e32 v117, v1
	v_pk_mul_f32 v[28:29], v[28:29], v[130:131] op_sel_hi:[1,0]
	v_pk_mul_f32 v[26:27], v[26:27], v[130:131] op_sel_hi:[1,0]
	v_mov_b32_e32 v115, v1
	v_pk_mul_f32 v[20:21], v[20:21], v[130:131] op_sel_hi:[1,0]
	v_pk_mul_f32 v[18:19], v[18:19], v[130:131] op_sel_hi:[1,0]
	v_mov_b32_e32 v111, v1
	v_pk_mul_f32 v[12:13], v[12:13], v[130:131] op_sel_hi:[1,0]
	v_pk_mul_f32 v[10:11], v[10:11], v[130:131] op_sel_hi:[1,0]
	s_waitcnt vmcnt(2)
	v_pk_mul_f32 v[62:63], v[62:63], v[134:135]
	v_pk_mul_f32 v[64:65], v[64:65], v[136:137]
	s_waitcnt vmcnt(1)
	v_pk_add_f32 v[136:137], v[138:139], 1.0 op_sel_hi:[1,0]
	v_pk_add_f32 v[134:135], v[140:141], 1.0 op_sel_hi:[1,0]
	s_waitcnt vmcnt(0)
	v_pk_fma_f32 v[62:63], v[62:63], v[136:137], v[142:143]
	v_pk_fma_f32 v[64:65], v[64:65], v[134:135], v[144:145]
	v_cvt_pk_bf16_f32 v134, v62, v63
	v_lshl_add_u64 v[62:63], v[106:107], 0, v[146:147]
	v_cvt_pk_bf16_f32 v135, v64, v65
	global_store_dwordx2 v[62:63], v[134:135], off
	global_load_dwordx4 v[134:137], v[82:83], off offset:1024
	v_lshl_add_u64 v[64:65], v[128:129], 0, v[124:125]
	global_load_dwordx4 v[138:141], v[64:65], off
	global_load_dwordx4 v[142:145], v[132:133], off offset:1024
	s_waitcnt vmcnt(2)
	v_pk_mul_f32 v[58:59], v[58:59], v[134:135]
	s_waitcnt vmcnt(1)
	v_pk_add_f32 v[134:135], v[138:139], 1.0 op_sel_hi:[1,0]
	v_pk_mul_f32 v[60:61], v[60:61], v[136:137]
	v_pk_add_f32 v[64:65], v[140:141], 1.0 op_sel_hi:[1,0]
	s_waitcnt vmcnt(0)
	v_pk_fma_f32 v[58:59], v[58:59], v[134:135], v[142:143]
	v_pk_fma_f32 v[60:61], v[60:61], v[64:65], v[144:145]
	v_cvt_pk_bf16_f32 v58, v58, v59
	v_lshl_add_u64 v[64:65], v[128:129], 0, v[122:123]
	v_cvt_pk_bf16_f32 v59, v60, v61
	global_store_dwordx2 v[62:63], v[58:59], off offset:512
	global_load_dwordx4 v[58:61], v[82:83], off offset:2048
	s_nop 0
	global_load_dwordx4 v[134:137], v[64:65], off
	global_load_dwordx4 v[138:141], v[132:133], off offset:2048
	s_waitcnt vmcnt(2)
; __device__ __forceinline__ unsigned cvt_pk_bf16(float lo, float hi) { unsigned r; asm volatile("v_cvt_pk_bf16_f32 %0, %1, %2" : "=v"(r) : "v"(lo), "v"(hi)); return r; }
; __device__ __forceinline__ void phase_norm(CArgs& a, int l, int which) {
;     ...
;         for (int u = 0; u < 2; ++u) { float ss = 0.f;
; #pragma unroll
;             for (int j = 0; j < 8; ++j) ss += (x[u][j].x * x[u][j].x + x[u][j].y * x[u][j].y) + (x[u][j].z * x[u][j].z + x[u][j].w * x[u][j].w);
;             const float rs = rsqrtf(wave_sum(ss) * (1.f / DM) + EPS);
;             if (!ok[u]) continue;
;             bf16_t* o = H + (size_t)(r0 + u * NGW) * DM;
; #pragma unroll
;             for (int j = 0; j < 8; ++j) { const int c = 4 * lane + 256 * j; const f32x4 g = *(const f32x4*)(gn + c), s1 = *(const f32x4*)(sc[u] + c), s0 = *(const f32x4*)(sh[u] + c);
;                 const f32x4 y = (x[u][j] * rs) * g * (1.f + s1) + s0;
;                 u32x2 w; w.x = cvt_pk_bf16(y.x, y.y); w.y = cvt_pk_bf16(y.z, y.w); *(u32x2*)(o + c) = w; } }
	v_pk_mul_f32 v[50:51], v[50:51], v[58:59]
	v_pk_mul_f32 v[52:53], v[52:53], v[60:61]
	s_waitcnt vmcnt(1)
	v_pk_add_f32 v[60:61], v[134:135], 1.0 op_sel_hi:[1,0]
	v_pk_add_f32 v[58:59], v[136:137], 1.0 op_sel_hi:[1,0]
	s_waitcnt vmcnt(0)
	v_pk_fma_f32 v[50:51], v[50:51], v[60:61], v[138:139]
	v_pk_fma_f32 v[52:53], v[52:53], v[58:59], v[140:141]
	v_cvt_pk_bf16_f32 v50, v50, v51
	v_lshl_add_u64 v[58:59], v[128:129], 0, v[120:121]
	v_cvt_pk_bf16_f32 v51, v52, v53
	global_store_dwordx2 v[62:63], v[50:51], off offset:1024
	global_load_dwordx4 v[50:53], v[82:83], off offset:3072
	s_nop 0
	global_load_dwordx4 v[58:61], v[58:59], off
	s_nop 0
	global_load_dwordx4 v[132:135], v[132:133], off offset:3072
	s_waitcnt vmcnt(2)
	v_pk_mul_f32 v[42:43], v[42:43], v[50:51]
	v_pk_mul_f32 v[44:45], v[44:45], v[52:53]
	s_waitcnt vmcnt(1)
	v_pk_add_f32 v[52:53], v[58:59], 1.0 op_sel_hi:[1,0]
	v_pk_add_f32 v[50:51], v[60:61], 1.0 op_sel_hi:[1,0]
	s_waitcnt vmcnt(0)
	v_pk_fma_f32 v[42:43], v[42:43], v[52:53], v[132:133]
	v_pk_fma_f32 v[44:45], v[44:45], v[50:51], v[134:135]
	v_cvt_pk_bf16_f32 v42, v42, v43
	v_lshl_add_u64 v[50:51], v[128:129], 0, v[118:119]
	v_cvt_pk_bf16_f32 v43, v44, v45
	global_store_dwordx2 v[62:63], v[42:43], off offset:1536
	global_load_dwordx4 v[42:45], v[92:93], off
	v_lshl_add_u64 v[58:59], v[126:127], 0, v[118:119]
	global_load_dwordx4 v[50:53], v[50:51], off
	s_waitcnt vmcnt(1)
	v_pk_mul_f32 v[34:35], v[34:35], v[42:43]
	global_load_dwordx4 v[58:61], v[58:59], off
	v_pk_mul_f32 v[36:37], v[36:37], v[44:45]
	s_waitcnt vmcnt(1)
	v_pk_add_f32 v[44:45], v[50:51], 1.0 op_sel_hi:[1,0]
	v_pk_add_f32 v[42:43], v[52:53], 1.0 op_sel_hi:[1,0]
	v_lshl_add_u64 v[50:51], v[126:127], 0, v[116:117]
	s_waitcnt vmcnt(0)
	v_pk_fma_f32 v[34:35], v[34:35], v[44:45], v[58:59]
	v_pk_fma_f32 v[36:37], v[36:37], v[42:43], v[60:61]
	v_cvt_pk_bf16_f32 v34, v34, v35
	v_lshl_add_u64 v[42:43], v[128:129], 0, v[116:117]
	v_cvt_pk_bf16_f32 v35, v36, v37
	global_store_dwordx2 v[62:63], v[34:35], off offset:2048
	global_load_dwordx4 v[34:37], v[96:97], off
	s_waitcnt vmcnt(0)
	v_pk_mul_f32 v[26:27], v[26:27], v[34:35]
	global_load_dwordx4 v[42:45], v[42:43], off
	v_pk_mul_f32 v[28:29], v[28:29], v[36:37]
	global_load_dwordx4 v[50:53], v[50:51], off
	s_waitcnt vmcnt(1)
	v_pk_add_f32 v[36:37], v[42:43], 1.0 op_sel_hi:[1,0]
	v_pk_add_f32 v[34:35], v[44:45], 1.0 op_sel_hi:[1,0]
	s_waitcnt vmcnt(0)
	v_pk_fma_f32 v[26:27], v[26:27], v[36:37], v[50:51]
	v_pk_fma_f32 v[28:29], v[28:29], v[34:35], v[52:53]
	v_cvt_pk_bf16_f32 v26, v26, v27
	v_lshl_add_u64 v[34:35], v[128:129], 0, v[114:115]
	v_cvt_pk_bf16_f32 v27, v28, v29
	global_store_dwordx2 v[62:63], v[26:27], off offset:2560
	global_load_dwordx4 v[26:29], v[100:101], off
	v_lshl_add_u64 v[42:43], v[126:127], 0, v[114:115]
	global_load_dwordx4 v[34:37], v[34:35], off
	s_waitcnt vmcnt(1)
	v_pk_mul_f32 v[18:19], v[18:19], v[26:27]
	global_load_dwordx4 v[42:45], v[42:43], off
	v_pk_mul_f32 v[20:21], v[20:21], v[28:29]
	s_waitcnt vmcnt(1)
	v_pk_add_f32 v[28:29], v[34:35], 1.0 op_sel_hi:[1,0]
	v_pk_add_f32 v[26:27], v[36:37], 1.0 op_sel_hi:[1,0]
	v_lshl_add_u64 v[34:35], v[126:127], 0, v[110:111]
	s_waitcnt vmcnt(0)
	v_pk_fma_f32 v[18:19], v[18:19], v[28:29], v[42:43]
	v_pk_fma_f32 v[20:21], v[20:21], v[26:27], v[44:45]
	v_cvt_pk_bf16_f32 v18, v18, v19
	v_lshl_add_u64 v[26:27], v[128:129], 0, v[110:111]
	v_cvt_pk_bf16_f32 v19, v20, v21
	global_store_dwordx2 v[62:63], v[18:19], off offset:3072
	global_load_dwordx4 v[18:21], v[104:105], off
	s_waitcnt vmcnt(0)
	v_pk_mul_f32 v[10:11], v[10:11], v[18:19]
	global_load_dwordx4 v[26:29], v[26:27], off
	v_pk_mul_f32 v[12:13], v[12:13], v[20:21]
	global_load_dwordx4 v[34:37], v[34:35], off
	s_waitcnt vmcnt(1)
	v_pk_add_f32 v[20:21], v[26:27], 1.0 op_sel_hi:[1,0]
	v_pk_add_f32 v[18:19], v[28:29], 1.0 op_sel_hi:[1,0]
	s_waitcnt vmcnt(0)
	v_pk_fma_f32 v[10:11], v[10:11], v[20:21], v[34:35]
	v_pk_fma_f32 v[12:13], v[12:13], v[18:19], v[36:37]
	v_cvt_pk_bf16_f32 v10, v10, v11
	s_nop 0
	v_cvt_pk_bf16_f32 v11, v12, v13
	global_store_dwordx2 v[62:63], v[10:11], off offset:3584
.LBB0_339:
	s_or_b64 exec, exec, s[20:21]
	v_mul_f32_e32 v10, v55, v55
	v_mul_f32_e32 v11, v57, v57
	v_fmac_f32_e32 v10, v54, v54
	v_fmac_f32_e32 v11, v56, v56
	v_add_f32_e32 v10, v10, v11
	v_mul_f32_e32 v11, v47, v47
	v_mul_f32_e32 v12, v49, v49
	v_fmac_f32_e32 v11, v46, v46
	v_fmac_f32_e32 v12, v48, v48
	v_add_f32_e32 v11, v11, v12
	v_add_f32_e32 v10, v11, v10
	v_mul_f32_e32 v11, v39, v39
	v_mul_f32_e32 v12, v41, v41
	v_fmac_f32_e32 v11, v38, v38
	v_fmac_f32_e32 v12, v40, v40
	v_add_f32_e32 v11, v11, v12
	v_add_f32_e32 v10, v10, v11
	v_mul_f32_e32 v11, v31, v31
	v_mul_f32_e32 v12, v33, v33
	v_fmac_f32_e32 v11, v30, v30
	v_fmac_f32_e32 v12, v32, v32
	v_add_f32_e32 v11, v11, v12
	v_add_f32_e32 v10, v10, v11
	v_mul_f32_e32 v11, v23, v23
	v_mul_f32_e32 v12, v25, v25
	v_fmac_f32_e32 v11, v22, v22
	v_fmac_f32_e32 v12, v24, v24
	v_add_f32_e32 v11, v11, v12
	v_add_f32_e32 v10, v10, v11
	v_mul_f32_e32 v11, v15, v15
	v_mul_f32_e32 v12, v17, v17
	v_fmac_f32_e32 v11, v14, v14
	v_fmac_f32_e32 v12, v16, v16
	v_add_f32_e32 v11, v11, v12
	v_add_f32_e32 v10, v10, v11
	v_mul_f32_e32 v11, v7, v7
	v_mul_f32_e32 v12, v9, v9
	v_fmac_f32_e32 v11, v6, v6
	v_fmac_f32_e32 v12, v8, v8
	v_add_f32_e32 v11, v11, v12
	v_add_f32_e32 v10, v10, v11
	v_mul_f32_e32 v11, v3, v3
	v_mul_f32_e32 v12, v5, v5
	v_fmac_f32_e32 v11, v2, v2
	v_fmac_f32_e32 v12, v4, v4
	v_add_f32_e32 v11, v11, v12
	v_add_f32_e32 v10, v10, v11
	s_nop 1
	s_and_b64 s[4:5], s[46:47], s[40:41]
	s_nor_b64 s[4:5], s[4:5], s[38:39]
	v_add_f32_dpp v10, v10, v10 quad_perm:[1,0,3,2] row_mask:0xf bank_mask:0xf
	s_nop 1
	v_add_f32_dpp v10, v10, v10 quad_perm:[2,3,0,1] row_mask:0xf bank_mask:0xf
	s_nop 1
	v_add_f32_dpp v10, v10, v10 row_half_mirror row_mask:0xf bank_mask:0xf
	s_nop 1
	v_add_f32_dpp v10, v10, v10 row_mirror row_mask:0xf bank_mask:0xf
	ds_bpermute_b32 v11, v91, v10
	s_waitcnt lgkmcnt(0)
	v_add_f32_e32 v18, v10, v11
	ds_bpermute_b32 v19, v95, v18
	s_and_saveexec_b64 s[20:21], s[4:5]
	s_cbranch_execz .LBB0_308
; __device__ __forceinline__ unsigned cvt_pk_bf16(float lo, float hi) { unsigned r; asm volatile("v_cvt_pk_bf16_f32 %0, %1, %2" : "=v"(r) : "v"(lo), "v"(hi)); return r; }
; __device__ __forceinline__ void phase_norm(CArgs& a, int l, int which) {
;     ...
;             if (!ok[u]) continue;
;             bf16_t* o = H + (size_t)(r0 + u * NGW) * DM;
; #pragma unroll
;             for (int j = 0; j < 8; ++j) { const int c = 4 * lane + 256 * j; const f32x4 g = *(const f32x4*)(gn + c), s1 = *(const f32x4*)(sc[u] + c), s0 = *(const f32x4*)(sh[u] + c);
;                 const f32x4 y = (x[u][j] * rs) * g * (1.f + s1) + s0;
;                 u32x2 w; w.x = cvt_pk_bf16(y.x, y.y); w.y = cvt_pk_bf16(y.z, y.w); *(u32x2*)(o + c) = w; } }
	v_mul_hi_i32_i24_e32 v11, 0xc000, v99
	v_mul_i32_i24_e32 v10, 0xc000, v99
	v_lshl_add_u64 v[10:11], s[72:73], 0, v[10:11]
	v_lshl_add_u64 v[12:13], v[10:11], 0, s[96:97]
	v_lshl_add_u64 v[26:27], v[12:13], 0, v[0:1]
	global_load_dwordx4 v[34:37], v[82:83], off
	global_load_dwordx4 v[42:45], v[26:27], off
	v_lshl_add_u64 v[26:27], v[10:11], 0, v[0:1]
	global_load_dwordx4 v[50:53], v[26:27], off
	s_waitcnt lgkmcnt(0)
	v_add_f32_e32 v18, v18, v19
	v_fmamk_f32 v18, v18, 0x3a000000, v216
	v_cmp_gt_f32_e32 vcc, s26, v18
	v_mul_f32_e32 v19, 0x4b800000, v18
	v_ashrrev_i32_e32 v113, 31, v112
	v_cndmask_b32_e32 v18, v18, v19, vcc
	v_rsq_f32_e32 v18, v18
	v_lshlrev_b64 v[20:21], 12, v[112:113]
	v_lshl_add_u64 v[20:21], v[106:107], 0, v[20:21]
	v_mov_b32_e32 v125, v1
	v_mul_f32_e32 v19, 0x45800000, v18
	v_cndmask_b32_e32 v18, v18, v19, vcc
	v_pk_mul_f32 v[54:55], v[54:55], v[18:19] op_sel_hi:[1,0]
	v_pk_mul_f32 v[28:29], v[56:57], v[18:19] op_sel_hi:[1,0]
	v_pk_mul_f32 v[46:47], v[46:47], v[18:19] op_sel_hi:[1,0]
	v_mov_b32_e32 v123, v1
	v_pk_mul_f32 v[38:39], v[38:39], v[18:19] op_sel_hi:[1,0]
	v_mov_b32_e32 v121, v1
	v_pk_mul_f32 v[32:33], v[32:33], v[18:19] op_sel_hi:[1,0]
	v_pk_mul_f32 v[30:31], v[30:31], v[18:19] op_sel_hi:[1,0]
	v_mov_b32_e32 v119, v1
	v_pk_mul_f32 v[24:25], v[24:25], v[18:19] op_sel_hi:[1,0]
	v_pk_mul_f32 v[22:23], v[22:23], v[18:19] op_sel_hi:[1,0]
	v_mov_b32_e32 v117, v1
	v_pk_mul_f32 v[16:17], v[16:17], v[18:19] op_sel_hi:[1,0]
	v_pk_mul_f32 v[14:15], v[14:15], v[18:19] op_sel_hi:[1,0]
	v_mov_b32_e32 v115, v1
	v_pk_mul_f32 v[8:9], v[8:9], v[18:19] op_sel_hi:[1,0]
	v_pk_mul_f32 v[6:7], v[6:7], v[18:19] op_sel_hi:[1,0]
	v_mov_b32_e32 v111, v1
	v_pk_mul_f32 v[4:5], v[4:5], v[18:19] op_sel_hi:[1,0]
	v_pk_mul_f32 v[2:3], v[2:3], v[18:19] op_sel_hi:[1,0]
	s_waitcnt vmcnt(2)
	v_pk_mul_f32 v[34:35], v[54:55], v[34:35]
	s_waitcnt vmcnt(1)
	v_pk_add_f32 v[42:43], v[42:43], 1.0 op_sel_hi:[1,0]
	v_pk_mul_f32 v[28:29], v[28:29], v[36:37]
	v_pk_add_f32 v[36:37], v[44:45], 1.0 op_sel_hi:[1,0]
	s_waitcnt vmcnt(0)
	v_pk_fma_f32 v[34:35], v[34:35], v[42:43], v[50:51]
	v_pk_fma_f32 v[28:29], v[28:29], v[36:37], v[52:53]
	v_cvt_pk_bf16_f32 v34, v34, v35
	s_nop 0
	v_cvt_pk_bf16_f32 v35, v28, v29
	global_store_dwordx2 v[20:21], v[34:35], off
	global_load_dwordx4 v[34:37], v[82:83], off offset:1024
	v_lshl_add_u64 v[28:29], v[12:13], 0, v[124:125]
	global_load_dwordx4 v[42:45], v[28:29], off
	global_load_dwordx4 v[50:53], v[26:27], off offset:1024
	v_pk_mul_f32 v[28:29], v[48:49], v[18:19] op_sel_hi:[1,0]
	s_waitcnt vmcnt(2)
	v_pk_mul_f32 v[34:35], v[46:47], v[34:35]
	s_waitcnt vmcnt(1)
	v_pk_add_f32 v[42:43], v[42:43], 1.0 op_sel_hi:[1,0]
	v_pk_mul_f32 v[28:29], v[28:29], v[36:37]
	v_pk_add_f32 v[36:37], v[44:45], 1.0 op_sel_hi:[1,0]
	s_waitcnt vmcnt(0)
	v_pk_fma_f32 v[34:35], v[34:35], v[42:43], v[50:51]
	v_pk_fma_f32 v[28:29], v[28:29], v[36:37], v[52:53]
	v_cvt_pk_bf16_f32 v34, v34, v35
	s_nop 0
	v_cvt_pk_bf16_f32 v35, v28, v29
	global_store_dwordx2 v[20:21], v[34:35], off offset:512
	global_load_dwordx4 v[34:37], v[82:83], off offset:2048
	v_lshl_add_u64 v[28:29], v[12:13], 0, v[122:123]
	global_load_dwordx4 v[42:45], v[28:29], off
	global_load_dwordx4 v[46:49], v[26:27], off offset:2048
	v_pk_mul_f32 v[28:29], v[40:41], v[18:19] op_sel_hi:[1,0]
	s_waitcnt vmcnt(2)
	v_pk_mul_f32 v[34:35], v[38:39], v[34:35]
	s_waitcnt vmcnt(1)
	v_pk_add_f32 v[38:39], v[42:43], 1.0 op_sel_hi:[1,0]
	v_pk_mul_f32 v[28:29], v[28:29], v[36:37]
	v_pk_add_f32 v[36:37], v[44:45], 1.0 op_sel_hi:[1,0]
	s_waitcnt vmcnt(0)
; __device__ __forceinline__ unsigned cvt_pk_bf16(float lo, float hi) { unsigned r; asm volatile("v_cvt_pk_bf16_f32 %0, %1, %2" : "=v"(r) : "v"(lo), "v"(hi)); return r; }
; __device__ __forceinline__ void phase_norm(CArgs& a, int l, int which) {
;     ...
; #pragma unroll
;             for (int j = 0; j < 8; ++j) { const int c = 4 * lane + 256 * j; const f32x4 g = *(const f32x4*)(gn + c), s1 = *(const f32x4*)(sc[u] + c), s0 = *(const f32x4*)(sh[u] + c);
;                 const f32x4 y = (x[u][j] * rs) * g * (1.f + s1) + s0;
;                 u32x2 w; w.x = cvt_pk_bf16(y.x, y.y); w.y = cvt_pk_bf16(y.z, y.w); *(u32x2*)(o + c) = w; } }
	v_pk_fma_f32 v[34:35], v[34:35], v[38:39], v[46:47]
	v_pk_fma_f32 v[28:29], v[28:29], v[36:37], v[48:49]
	v_cvt_pk_bf16_f32 v34, v34, v35
	s_nop 0
	v_cvt_pk_bf16_f32 v35, v28, v29
	global_store_dwordx2 v[20:21], v[34:35], off offset:1024
	global_load_dwordx4 v[34:37], v[82:83], off offset:3072
	v_lshl_add_u64 v[28:29], v[12:13], 0, v[120:121]
	global_load_dwordx4 v[38:41], v[28:29], off
	s_nop 0
	global_load_dwordx4 v[26:29], v[26:27], off offset:3072
	s_waitcnt vmcnt(2)
	v_pk_mul_f32 v[30:31], v[30:31], v[34:35]
	v_pk_mul_f32 v[32:33], v[32:33], v[36:37]
	s_waitcnt vmcnt(1)
	v_pk_add_f32 v[36:37], v[38:39], 1.0 op_sel_hi:[1,0]
	v_pk_add_f32 v[34:35], v[40:41], 1.0 op_sel_hi:[1,0]
	s_waitcnt vmcnt(0)
	v_pk_fma_f32 v[26:27], v[30:31], v[36:37], v[26:27]
	v_pk_fma_f32 v[28:29], v[32:33], v[34:35], v[28:29]
	v_cvt_pk_bf16_f32 v26, v26, v27
	v_lshl_add_u64 v[30:31], v[12:13], 0, v[118:119]
	v_cvt_pk_bf16_f32 v27, v28, v29
	global_store_dwordx2 v[20:21], v[26:27], off offset:1536
	global_load_dwordx4 v[26:29], v[92:93], off
	v_lshl_add_u64 v[34:35], v[10:11], 0, v[118:119]
	global_load_dwordx4 v[30:33], v[30:31], off
	s_waitcnt vmcnt(1)
	v_pk_mul_f32 v[22:23], v[22:23], v[26:27]
	global_load_dwordx4 v[34:37], v[34:35], off
	v_pk_mul_f32 v[24:25], v[24:25], v[28:29]
	s_waitcnt vmcnt(1)
	v_pk_add_f32 v[28:29], v[30:31], 1.0 op_sel_hi:[1,0]
	v_pk_add_f32 v[26:27], v[32:33], 1.0 op_sel_hi:[1,0]
	v_lshl_add_u64 v[30:31], v[10:11], 0, v[116:117]
	s_waitcnt vmcnt(0)
	v_pk_fma_f32 v[22:23], v[22:23], v[28:29], v[34:35]
	v_pk_fma_f32 v[24:25], v[24:25], v[26:27], v[36:37]
	v_cvt_pk_bf16_f32 v22, v22, v23
	v_lshl_add_u64 v[26:27], v[12:13], 0, v[116:117]
	v_cvt_pk_bf16_f32 v23, v24, v25
	global_store_dwordx2 v[20:21], v[22:23], off offset:2048
	global_load_dwordx4 v[22:25], v[96:97], off
	s_waitcnt vmcnt(0)
	v_pk_mul_f32 v[14:15], v[14:15], v[22:23]
	global_load_dwordx4 v[26:29], v[26:27], off
	v_pk_mul_f32 v[16:17], v[16:17], v[24:25]
	global_load_dwordx4 v[30:33], v[30:31], off
	s_waitcnt vmcnt(1)
	v_pk_add_f32 v[24:25], v[26:27], 1.0 op_sel_hi:[1,0]
	v_pk_add_f32 v[22:23], v[28:29], 1.0 op_sel_hi:[1,0]
	s_waitcnt vmcnt(0)
	v_pk_fma_f32 v[14:15], v[14:15], v[24:25], v[30:31]
	v_pk_fma_f32 v[16:17], v[16:17], v[22:23], v[32:33]
	v_cvt_pk_bf16_f32 v14, v14, v15
	v_lshl_add_u64 v[22:23], v[12:13], 0, v[114:115]
	v_cvt_pk_bf16_f32 v15, v16, v17
	global_store_dwordx2 v[20:21], v[14:15], off offset:2560
	global_load_dwordx4 v[14:17], v[100:101], off
	v_lshl_add_u64 v[26:27], v[10:11], 0, v[114:115]
	global_load_dwordx4 v[22:25], v[22:23], off
	v_lshl_add_u64 v[12:13], v[12:13], 0, v[110:111]
	global_load_dwordx4 v[26:29], v[26:27], off
	v_lshl_add_u64 v[10:11], v[10:11], 0, v[110:111]
	s_waitcnt vmcnt(2)
	v_pk_mul_f32 v[6:7], v[6:7], v[14:15]
	v_pk_mul_f32 v[8:9], v[8:9], v[16:17]
	s_waitcnt vmcnt(1)
	v_pk_add_f32 v[16:17], v[22:23], 1.0 op_sel_hi:[1,0]
	v_pk_add_f32 v[14:15], v[24:25], 1.0 op_sel_hi:[1,0]
	s_waitcnt vmcnt(0)
	v_pk_fma_f32 v[6:7], v[6:7], v[16:17], v[26:27]
	v_pk_fma_f32 v[8:9], v[8:9], v[14:15], v[28:29]
	v_cvt_pk_bf16_f32 v6, v6, v7
	s_nop 0
	v_cvt_pk_bf16_f32 v7, v8, v9
	global_store_dwordx2 v[20:21], v[6:7], off offset:3072
	global_load_dwordx4 v[6:9], v[104:105], off
	s_waitcnt vmcnt(0)
	v_pk_mul_f32 v[2:3], v[2:3], v[6:7]
	global_load_dwordx4 v[12:15], v[12:13], off
	v_pk_mul_f32 v[4:5], v[4:5], v[8:9]
	global_load_dwordx4 v[22:25], v[10:11], off
	s_waitcnt vmcnt(1)
	v_pk_add_f32 v[8:9], v[12:13], 1.0 op_sel_hi:[1,0]
	v_pk_add_f32 v[6:7], v[14:15], 1.0 op_sel_hi:[1,0]
	s_waitcnt vmcnt(0)
	v_pk_fma_f32 v[2:3], v[2:3], v[8:9], v[22:23]
	v_pk_fma_f32 v[4:5], v[4:5], v[6:7], v[24:25]
	v_cvt_pk_bf16_f32 v2, v2, v3
	s_nop 0
	v_cvt_pk_bf16_f32 v3, v4, v5
	global_store_dwordx2 v[20:21], v[2:3], off offset:3584
	s_branch .LBB0_308
